# s5pre Bt2 table emission rewritten divergence-free (Toeplitz part: 2 ds_read_b128 + select per 16-byte chunk; state-readout part with hoisted C rows)
# speedup vs baseline: 1.0093x; 1.0074x over previous
; DI u32x4 pack8(const float* f) { u32x4 w; w.x = pk2(f[0], f[1]); w.y = pk2(f[2], f[3]); w.z = pk2(f[4], f[5]); w.w = pk2(f[6], f[7]); return w; }
; DI void phase_s5pre(LAS unsigned char* lds, PP p, int l, int bid, int nblk) {
;     ...
;         for (int id = tid; id < 512 * 80; id += NTHR) { const int n = id / 80, oc = id % 80, t = n >> 4, ho = n & 15; float f[8];
;             if (oc < 64) { const int s = oc >> 1, hi0 = (oc & 1) * 8;
;                 for (int i = 0; i < 8; ++i) f[i] = (s <= t) ? kt[(t - s) * 256 + ho * 16 + hi0 + i] : 0.f;
;             } else { for (int i = 0; i < 8; ++i) { const int cc = (oc - 64) * 8 + i, ri = cc >> 6, pp = cc & 63;
;                 const float ar = apr[(t + 1) * 64 + pp], ai = api[(t + 1) * 64 + pp], cr = ccr[ho * 64 + pp], ci = cci[ho * 64 + pp];
;                 f[i] = ri == 0 ? (cr * ar - ci * ai) : -(cr * ai + ci * ar); } }
;             *(u32x4*)(bt2 + ((size_t)g * 512 + n) * 640 + oc * 8) = pack8(f); }
.LBB0_260:
	s_or_b64 exec, exec, s[2:3]
	s_waitcnt lgkmcnt(0)
	s_barrier
	s_and_saveexec_b64 s[2:3], s[28:29]
	s_cbranch_execz .LBB0_283
	s_mul_i32 s34, s20, 0xa0000
	s_add_u32 s34, s58, s34
	s_addc_u32 s35, s59, 0
	s_mov_b64 s[38:39], 0x2800
	s_mov_b64 s[40:41], 0xa000
	v_lshrrev_b32_e32 v60, 6, v201
	v_and_b32_e32 v61, 63, v201
	v_lshrrev_b32_e32 v62, 1, v61
	v_and_b32_e32 v63, 1, v61
	v_lshlrev_b32_e32 v63, 5, v63
	v_lshl_add_u32 v64, v60, 6, v63
	v_add_u32_e32 v64, 0x8200, v64
	v_mul_u32_u24_e32 v68, 0x500, v60
	v_lshl_add_u32 v68, v61, 4, v68
	v_mov_b32_e32 v69, 0
	v_lshl_add_u64 v[68:69], s[34:35], 0, v[68:69]
	v_and_b32_e32 v148, 3, v60
	v_lshlrev_b32_e32 v148, 2, v148
	v_lshrrev_b32_e32 v149, 4, v61
	v_add_u32_e32 v148, v148, v149
	v_and_b32_e32 v149, 7, v61
	v_lshlrev_b32_e32 v149, 5, v149
	v_bfe_u32 v150, v61, 3, 1
	v_lshrrev_b32_e32 v151, 2, v60
	v_lshl_add_u32 v114, v148, 8, v149
	ds_read_b128 v[116:119], v114 offset:25088
	ds_read_b128 v[120:123], v114 offset:25104
	ds_read_b128 v[124:127], v114 offset:29184
	ds_read_b128 v[128:131], v114 offset:29200
	v_lshl_add_u32 v112, v151, 8, v149
	v_add_u32_e32 v112, 0x100, v112
	v_mul_u32_u24_e32 v152, 0x2100, v150
	v_add_u32_e32 v113, 0x2100, v112
	v_sub_u32_e32 v113, v113, v152
	v_add_u32_e32 v112, v112, v152
	v_lshlrev_b32_e32 v115, 31, v150
	v_lshrrev_b32_e32 v153, 4, v201
	v_mul_u32_u24_e32 v172, 0x500, v153
	v_and_b32_e32 v153, 15, v61
	v_lshl_add_u32 v172, v153, 4, v172
	v_add_u32_e32 v172, 0x400, v172
	v_mov_b32_e32 v173, 0
	v_lshl_add_u64 v[172:173], s[34:35], 0, v[172:173]
	s_waitcnt lgkmcnt(0)
	v_xor_b32_e32 v116, v115, v116
	v_xor_b32_e32 v117, v115, v117
	v_xor_b32_e32 v118, v115, v118
	v_xor_b32_e32 v119, v115, v119
	v_xor_b32_e32 v120, v115, v120
	v_xor_b32_e32 v121, v115, v121
	v_xor_b32_e32 v122, v115, v122
	v_xor_b32_e32 v123, v115, v123
	v_sub_u32_e32 v65, 0, v62
	v_max_i32_e32 v65, 0, v65
	v_lshl_add_u32 v66, v65, 10, v64
	ds_read_b128 v[72:75], v66
	ds_read_b128 v[76:79], v66 offset:16
	ds_read_b128 v[80:83], v66 offset:512
	ds_read_b128 v[84:87], v66 offset:528
	v_sub_u32_e32 v65, 1, v62
	v_max_i32_e32 v65, 0, v65
	v_lshl_add_u32 v66, v65, 10, v64
	ds_read_b128 v[88:91], v66
	ds_read_b128 v[92:95], v66 offset:16
	ds_read_b128 v[96:99], v66 offset:512
	ds_read_b128 v[100:103], v66 offset:528
	s_waitcnt lgkmcnt(4)
	v_cmp_ge_u32_e64 s[36:37], 0, v62
	v_cvt_pk_bf16_f32 v104, v72, v73
	v_cvt_pk_bf16_f32 v105, v74, v75
	v_cvt_pk_bf16_f32 v106, v76, v77
	v_cvt_pk_bf16_f32 v107, v78, v79
	v_cndmask_b32_e64 v104, 0, v104, s[36:37]
	v_cndmask_b32_e64 v105, 0, v105, s[36:37]
	v_cndmask_b32_e64 v106, 0, v106, s[36:37]
	v_cndmask_b32_e64 v107, 0, v107, s[36:37]
	global_store_dwordx4 v[68:69], v[104:107], off
	v_lshl_add_u64 v[68:69], v[68:69], 0, s[38:39]
	v_cvt_pk_bf16_f32 v108, v80, v81
	v_cvt_pk_bf16_f32 v109, v82, v83
	v_cvt_pk_bf16_f32 v110, v84, v85
	v_cvt_pk_bf16_f32 v111, v86, v87
	v_cndmask_b32_e64 v108, 0, v108, s[36:37]
	v_cndmask_b32_e64 v109, 0, v109, s[36:37]
	v_cndmask_b32_e64 v110, 0, v110, s[36:37]
	v_cndmask_b32_e64 v111, 0, v111, s[36:37]
	global_store_dwordx4 v[68:69], v[108:111], off
	v_lshl_add_u64 v[68:69], v[68:69], 0, s[38:39]
	v_sub_u32_e32 v65, 2, v62
	v_max_i32_e32 v65, 0, v65
	v_lshl_add_u32 v66, v65, 10, v64
	ds_read_b128 v[72:75], v66
	ds_read_b128 v[76:79], v66 offset:16
	ds_read_b128 v[80:83], v66 offset:512
	ds_read_b128 v[84:87], v66 offset:528
	s_waitcnt lgkmcnt(4)
	v_cmp_ge_u32_e64 s[36:37], 1, v62
	v_cvt_pk_bf16_f32 v104, v88, v89
	v_cvt_pk_bf16_f32 v105, v90, v91
	v_cvt_pk_bf16_f32 v106, v92, v93
	v_cvt_pk_bf16_f32 v107, v94, v95
	v_cndmask_b32_e64 v104, 0, v104, s[36:37]
	v_cndmask_b32_e64 v105, 0, v105, s[36:37]
	v_cndmask_b32_e64 v106, 0, v106, s[36:37]
	v_cndmask_b32_e64 v107, 0, v107, s[36:37]
	global_store_dwordx4 v[68:69], v[104:107], off
	v_lshl_add_u64 v[68:69], v[68:69], 0, s[38:39]
	v_cvt_pk_bf16_f32 v108, v96, v97
	v_cvt_pk_bf16_f32 v109, v98, v99
	v_cvt_pk_bf16_f32 v110, v100, v101
	v_cvt_pk_bf16_f32 v111, v102, v103
	v_cndmask_b32_e64 v108, 0, v108, s[36:37]
	v_cndmask_b32_e64 v109, 0, v109, s[36:37]
	v_cndmask_b32_e64 v110, 0, v110, s[36:37]
	v_cndmask_b32_e64 v111, 0, v111, s[36:37]
	global_store_dwordx4 v[68:69], v[108:111], off
	v_lshl_add_u64 v[68:69], v[68:69], 0, s[38:39]
	v_sub_u32_e32 v65, 3, v62
	v_max_i32_e32 v65, 0, v65
	v_lshl_add_u32 v66, v65, 10, v64
	ds_read_b128 v[88:91], v66
	ds_read_b128 v[92:95], v66 offset:16
	ds_read_b128 v[96:99], v66 offset:512
	ds_read_b128 v[100:103], v66 offset:528
	s_waitcnt lgkmcnt(4)
	v_cmp_ge_u32_e64 s[36:37], 2, v62
	v_cvt_pk_bf16_f32 v104, v72, v73
	v_cvt_pk_bf16_f32 v105, v74, v75
	v_cvt_pk_bf16_f32 v106, v76, v77
	v_cvt_pk_bf16_f32 v107, v78, v79
	v_cndmask_b32_e64 v104, 0, v104, s[36:37]
	v_cndmask_b32_e64 v105, 0, v105, s[36:37]
	v_cndmask_b32_e64 v106, 0, v106, s[36:37]
	v_cndmask_b32_e64 v107, 0, v107, s[36:37]
	global_store_dwordx4 v[68:69], v[104:107], off
	v_lshl_add_u64 v[68:69], v[68:69], 0, s[38:39]
	v_cvt_pk_bf16_f32 v108, v80, v81
	v_cvt_pk_bf16_f32 v109, v82, v83
	v_cvt_pk_bf16_f32 v110, v84, v85
	v_cvt_pk_bf16_f32 v111, v86, v87
	v_cndmask_b32_e64 v108, 0, v108, s[36:37]
	v_cndmask_b32_e64 v109, 0, v109, s[36:37]
	v_cndmask_b32_e64 v110, 0, v110, s[36:37]
	v_cndmask_b32_e64 v111, 0, v111, s[36:37]
	global_store_dwordx4 v[68:69], v[108:111], off
	v_lshl_add_u64 v[68:69], v[68:69], 0, s[38:39]
	v_sub_u32_e32 v65, 4, v62
	v_max_i32_e32 v65, 0, v65
	v_lshl_add_u32 v66, v65, 10, v64
	ds_read_b128 v[72:75], v66
	ds_read_b128 v[76:79], v66 offset:16
	ds_read_b128 v[80:83], v66 offset:512
	ds_read_b128 v[84:87], v66 offset:528
	s_waitcnt lgkmcnt(4)
; DI u32x4 pack8(const float* f) { u32x4 w; w.x = pk2(f[0], f[1]); w.y = pk2(f[2], f[3]); w.z = pk2(f[4], f[5]); w.w = pk2(f[6], f[7]); return w; }
; DI void phase_s5pre(LAS unsigned char* lds, PP p, int l, int bid, int nblk) {
;     ...
;         for (int id = tid; id < 512 * 80; id += NTHR) { const int n = id / 80, oc = id % 80, t = n >> 4, ho = n & 15; float f[8];
;             if (oc < 64) { const int s = oc >> 1, hi0 = (oc & 1) * 8;
;                 for (int i = 0; i < 8; ++i) f[i] = (s <= t) ? kt[(t - s) * 256 + ho * 16 + hi0 + i] : 0.f;
;             } else { for (int i = 0; i < 8; ++i) { const int cc = (oc - 64) * 8 + i, ri = cc >> 6, pp = cc & 63;
;                 const float ar = apr[(t + 1) * 64 + pp], ai = api[(t + 1) * 64 + pp], cr = ccr[ho * 64 + pp], ci = cci[ho * 64 + pp];
;                 f[i] = ri == 0 ? (cr * ar - ci * ai) : -(cr * ai + ci * ar); } }
;             *(u32x4*)(bt2 + ((size_t)g * 512 + n) * 640 + oc * 8) = pack8(f); }
	v_cmp_ge_u32_e64 s[36:37], 3, v62
	v_cvt_pk_bf16_f32 v104, v88, v89
	v_cvt_pk_bf16_f32 v105, v90, v91
	v_cvt_pk_bf16_f32 v106, v92, v93
	v_cvt_pk_bf16_f32 v107, v94, v95
	v_cndmask_b32_e64 v104, 0, v104, s[36:37]
	v_cndmask_b32_e64 v105, 0, v105, s[36:37]
	v_cndmask_b32_e64 v106, 0, v106, s[36:37]
	v_cndmask_b32_e64 v107, 0, v107, s[36:37]
	global_store_dwordx4 v[68:69], v[104:107], off
	v_lshl_add_u64 v[68:69], v[68:69], 0, s[38:39]
	v_cvt_pk_bf16_f32 v108, v96, v97
	v_cvt_pk_bf16_f32 v109, v98, v99
	v_cvt_pk_bf16_f32 v110, v100, v101
	v_cvt_pk_bf16_f32 v111, v102, v103
	v_cndmask_b32_e64 v108, 0, v108, s[36:37]
	v_cndmask_b32_e64 v109, 0, v109, s[36:37]
	v_cndmask_b32_e64 v110, 0, v110, s[36:37]
	v_cndmask_b32_e64 v111, 0, v111, s[36:37]
	global_store_dwordx4 v[68:69], v[108:111], off
	v_lshl_add_u64 v[68:69], v[68:69], 0, s[38:39]
	v_sub_u32_e32 v65, 5, v62
	v_max_i32_e32 v65, 0, v65
	v_lshl_add_u32 v66, v65, 10, v64
	ds_read_b128 v[88:91], v66
	ds_read_b128 v[92:95], v66 offset:16
	ds_read_b128 v[96:99], v66 offset:512
	ds_read_b128 v[100:103], v66 offset:528
	s_waitcnt lgkmcnt(4)
	v_cmp_ge_u32_e64 s[36:37], 4, v62
	v_cvt_pk_bf16_f32 v104, v72, v73
	v_cvt_pk_bf16_f32 v105, v74, v75
	v_cvt_pk_bf16_f32 v106, v76, v77
	v_cvt_pk_bf16_f32 v107, v78, v79
	v_cndmask_b32_e64 v104, 0, v104, s[36:37]
	v_cndmask_b32_e64 v105, 0, v105, s[36:37]
	v_cndmask_b32_e64 v106, 0, v106, s[36:37]
	v_cndmask_b32_e64 v107, 0, v107, s[36:37]
	global_store_dwordx4 v[68:69], v[104:107], off
	v_lshl_add_u64 v[68:69], v[68:69], 0, s[38:39]
	v_cvt_pk_bf16_f32 v108, v80, v81
	v_cvt_pk_bf16_f32 v109, v82, v83
	v_cvt_pk_bf16_f32 v110, v84, v85
	v_cvt_pk_bf16_f32 v111, v86, v87
	v_cndmask_b32_e64 v108, 0, v108, s[36:37]
	v_cndmask_b32_e64 v109, 0, v109, s[36:37]
	v_cndmask_b32_e64 v110, 0, v110, s[36:37]
	v_cndmask_b32_e64 v111, 0, v111, s[36:37]
	global_store_dwordx4 v[68:69], v[108:111], off
	v_lshl_add_u64 v[68:69], v[68:69], 0, s[38:39]
	v_sub_u32_e32 v65, 6, v62
	v_max_i32_e32 v65, 0, v65
	v_lshl_add_u32 v66, v65, 10, v64
	ds_read_b128 v[72:75], v66
	ds_read_b128 v[76:79], v66 offset:16
	ds_read_b128 v[80:83], v66 offset:512
	ds_read_b128 v[84:87], v66 offset:528
	s_waitcnt lgkmcnt(4)
	v_cmp_ge_u32_e64 s[36:37], 5, v62
	v_cvt_pk_bf16_f32 v104, v88, v89
	v_cvt_pk_bf16_f32 v105, v90, v91
	v_cvt_pk_bf16_f32 v106, v92, v93
	v_cvt_pk_bf16_f32 v107, v94, v95
	v_cndmask_b32_e64 v104, 0, v104, s[36:37]
	v_cndmask_b32_e64 v105, 0, v105, s[36:37]
	v_cndmask_b32_e64 v106, 0, v106, s[36:37]
	v_cndmask_b32_e64 v107, 0, v107, s[36:37]
	global_store_dwordx4 v[68:69], v[104:107], off
	v_lshl_add_u64 v[68:69], v[68:69], 0, s[38:39]
	v_cvt_pk_bf16_f32 v108, v96, v97
	v_cvt_pk_bf16_f32 v109, v98, v99
	v_cvt_pk_bf16_f32 v110, v100, v101
	v_cvt_pk_bf16_f32 v111, v102, v103
	v_cndmask_b32_e64 v108, 0, v108, s[36:37]
	v_cndmask_b32_e64 v109, 0, v109, s[36:37]
	v_cndmask_b32_e64 v110, 0, v110, s[36:37]
	v_cndmask_b32_e64 v111, 0, v111, s[36:37]
	global_store_dwordx4 v[68:69], v[108:111], off
	v_lshl_add_u64 v[68:69], v[68:69], 0, s[38:39]
	v_sub_u32_e32 v65, 7, v62
	v_max_i32_e32 v65, 0, v65
	v_lshl_add_u32 v66, v65, 10, v64
	ds_read_b128 v[88:91], v66
	ds_read_b128 v[92:95], v66 offset:16
	ds_read_b128 v[96:99], v66 offset:512
	ds_read_b128 v[100:103], v66 offset:528
	s_waitcnt lgkmcnt(4)
	v_cmp_ge_u32_e64 s[36:37], 6, v62
	v_cvt_pk_bf16_f32 v104, v72, v73
	v_cvt_pk_bf16_f32 v105, v74, v75
	v_cvt_pk_bf16_f32 v106, v76, v77
	v_cvt_pk_bf16_f32 v107, v78, v79
	v_cndmask_b32_e64 v104, 0, v104, s[36:37]
	v_cndmask_b32_e64 v105, 0, v105, s[36:37]
	v_cndmask_b32_e64 v106, 0, v106, s[36:37]
	v_cndmask_b32_e64 v107, 0, v107, s[36:37]
	global_store_dwordx4 v[68:69], v[104:107], off
	v_lshl_add_u64 v[68:69], v[68:69], 0, s[38:39]
	v_cvt_pk_bf16_f32 v108, v80, v81
	v_cvt_pk_bf16_f32 v109, v82, v83
	v_cvt_pk_bf16_f32 v110, v84, v85
	v_cvt_pk_bf16_f32 v111, v86, v87
	v_cndmask_b32_e64 v108, 0, v108, s[36:37]
	v_cndmask_b32_e64 v109, 0, v109, s[36:37]
	v_cndmask_b32_e64 v110, 0, v110, s[36:37]
	v_cndmask_b32_e64 v111, 0, v111, s[36:37]
	global_store_dwordx4 v[68:69], v[108:111], off
	v_lshl_add_u64 v[68:69], v[68:69], 0, s[38:39]
	v_sub_u32_e32 v65, 8, v62
	v_max_i32_e32 v65, 0, v65
	v_lshl_add_u32 v66, v65, 10, v64
	ds_read_b128 v[72:75], v66
	ds_read_b128 v[76:79], v66 offset:16
	ds_read_b128 v[80:83], v66 offset:512
	ds_read_b128 v[84:87], v66 offset:528
	s_waitcnt lgkmcnt(4)
	v_cmp_ge_u32_e64 s[36:37], 7, v62
	v_cvt_pk_bf16_f32 v104, v88, v89
	v_cvt_pk_bf16_f32 v105, v90, v91
	v_cvt_pk_bf16_f32 v106, v92, v93
	v_cvt_pk_bf16_f32 v107, v94, v95
	v_cndmask_b32_e64 v104, 0, v104, s[36:37]
	v_cndmask_b32_e64 v105, 0, v105, s[36:37]
	v_cndmask_b32_e64 v106, 0, v106, s[36:37]
	v_cndmask_b32_e64 v107, 0, v107, s[36:37]
	global_store_dwordx4 v[68:69], v[104:107], off
	v_lshl_add_u64 v[68:69], v[68:69], 0, s[38:39]
	v_cvt_pk_bf16_f32 v108, v96, v97
	v_cvt_pk_bf16_f32 v109, v98, v99
	v_cvt_pk_bf16_f32 v110, v100, v101
	v_cvt_pk_bf16_f32 v111, v102, v103
	v_cndmask_b32_e64 v108, 0, v108, s[36:37]
	v_cndmask_b32_e64 v109, 0, v109, s[36:37]
	v_cndmask_b32_e64 v110, 0, v110, s[36:37]
	v_cndmask_b32_e64 v111, 0, v111, s[36:37]
	global_store_dwordx4 v[68:69], v[108:111], off
	v_lshl_add_u64 v[68:69], v[68:69], 0, s[38:39]
	v_sub_u32_e32 v65, 9, v62
	v_max_i32_e32 v65, 0, v65
	v_lshl_add_u32 v66, v65, 10, v64
	ds_read_b128 v[88:91], v66
	ds_read_b128 v[92:95], v66 offset:16
	ds_read_b128 v[96:99], v66 offset:512
	ds_read_b128 v[100:103], v66 offset:528
	s_waitcnt lgkmcnt(4)
; DI u32x4 pack8(const float* f) { u32x4 w; w.x = pk2(f[0], f[1]); w.y = pk2(f[2], f[3]); w.z = pk2(f[4], f[5]); w.w = pk2(f[6], f[7]); return w; }
; DI void phase_s5pre(LAS unsigned char* lds, PP p, int l, int bid, int nblk) {
;     ...
;         for (int id = tid; id < 512 * 80; id += NTHR) { const int n = id / 80, oc = id % 80, t = n >> 4, ho = n & 15; float f[8];
;             if (oc < 64) { const int s = oc >> 1, hi0 = (oc & 1) * 8;
;                 for (int i = 0; i < 8; ++i) f[i] = (s <= t) ? kt[(t - s) * 256 + ho * 16 + hi0 + i] : 0.f;
;             } else { for (int i = 0; i < 8; ++i) { const int cc = (oc - 64) * 8 + i, ri = cc >> 6, pp = cc & 63;
;                 const float ar = apr[(t + 1) * 64 + pp], ai = api[(t + 1) * 64 + pp], cr = ccr[ho * 64 + pp], ci = cci[ho * 64 + pp];
;                 f[i] = ri == 0 ? (cr * ar - ci * ai) : -(cr * ai + ci * ar); } }
;             *(u32x4*)(bt2 + ((size_t)g * 512 + n) * 640 + oc * 8) = pack8(f); }
	v_cmp_ge_u32_e64 s[36:37], 8, v62
	v_cvt_pk_bf16_f32 v104, v72, v73
	v_cvt_pk_bf16_f32 v105, v74, v75
	v_cvt_pk_bf16_f32 v106, v76, v77
	v_cvt_pk_bf16_f32 v107, v78, v79
	v_cndmask_b32_e64 v104, 0, v104, s[36:37]
	v_cndmask_b32_e64 v105, 0, v105, s[36:37]
	v_cndmask_b32_e64 v106, 0, v106, s[36:37]
	v_cndmask_b32_e64 v107, 0, v107, s[36:37]
	global_store_dwordx4 v[68:69], v[104:107], off
	v_lshl_add_u64 v[68:69], v[68:69], 0, s[38:39]
	v_cvt_pk_bf16_f32 v108, v80, v81
	v_cvt_pk_bf16_f32 v109, v82, v83
	v_cvt_pk_bf16_f32 v110, v84, v85
	v_cvt_pk_bf16_f32 v111, v86, v87
	v_cndmask_b32_e64 v108, 0, v108, s[36:37]
	v_cndmask_b32_e64 v109, 0, v109, s[36:37]
	v_cndmask_b32_e64 v110, 0, v110, s[36:37]
	v_cndmask_b32_e64 v111, 0, v111, s[36:37]
	global_store_dwordx4 v[68:69], v[108:111], off
	v_lshl_add_u64 v[68:69], v[68:69], 0, s[38:39]
	v_sub_u32_e32 v65, 10, v62
	v_max_i32_e32 v65, 0, v65
	v_lshl_add_u32 v66, v65, 10, v64
	ds_read_b128 v[72:75], v66
	ds_read_b128 v[76:79], v66 offset:16
	ds_read_b128 v[80:83], v66 offset:512
	ds_read_b128 v[84:87], v66 offset:528
	s_waitcnt lgkmcnt(4)
	v_cmp_ge_u32_e64 s[36:37], 9, v62
	v_cvt_pk_bf16_f32 v104, v88, v89
	v_cvt_pk_bf16_f32 v105, v90, v91
	v_cvt_pk_bf16_f32 v106, v92, v93
	v_cvt_pk_bf16_f32 v107, v94, v95
	v_cndmask_b32_e64 v104, 0, v104, s[36:37]
	v_cndmask_b32_e64 v105, 0, v105, s[36:37]
	v_cndmask_b32_e64 v106, 0, v106, s[36:37]
	v_cndmask_b32_e64 v107, 0, v107, s[36:37]
	global_store_dwordx4 v[68:69], v[104:107], off
	v_lshl_add_u64 v[68:69], v[68:69], 0, s[38:39]
	v_cvt_pk_bf16_f32 v108, v96, v97
	v_cvt_pk_bf16_f32 v109, v98, v99
	v_cvt_pk_bf16_f32 v110, v100, v101
	v_cvt_pk_bf16_f32 v111, v102, v103
	v_cndmask_b32_e64 v108, 0, v108, s[36:37]
	v_cndmask_b32_e64 v109, 0, v109, s[36:37]
	v_cndmask_b32_e64 v110, 0, v110, s[36:37]
	v_cndmask_b32_e64 v111, 0, v111, s[36:37]
	global_store_dwordx4 v[68:69], v[108:111], off
	v_lshl_add_u64 v[68:69], v[68:69], 0, s[38:39]
	v_sub_u32_e32 v65, 11, v62
	v_max_i32_e32 v65, 0, v65
	v_lshl_add_u32 v66, v65, 10, v64
	ds_read_b128 v[88:91], v66
	ds_read_b128 v[92:95], v66 offset:16
	ds_read_b128 v[96:99], v66 offset:512
	ds_read_b128 v[100:103], v66 offset:528
	s_waitcnt lgkmcnt(4)
	v_cmp_ge_u32_e64 s[36:37], 10, v62
	v_cvt_pk_bf16_f32 v104, v72, v73
	v_cvt_pk_bf16_f32 v105, v74, v75
	v_cvt_pk_bf16_f32 v106, v76, v77
	v_cvt_pk_bf16_f32 v107, v78, v79
	v_cndmask_b32_e64 v104, 0, v104, s[36:37]
	v_cndmask_b32_e64 v105, 0, v105, s[36:37]
	v_cndmask_b32_e64 v106, 0, v106, s[36:37]
	v_cndmask_b32_e64 v107, 0, v107, s[36:37]
	global_store_dwordx4 v[68:69], v[104:107], off
	v_lshl_add_u64 v[68:69], v[68:69], 0, s[38:39]
	v_cvt_pk_bf16_f32 v108, v80, v81
	v_cvt_pk_bf16_f32 v109, v82, v83
	v_cvt_pk_bf16_f32 v110, v84, v85
	v_cvt_pk_bf16_f32 v111, v86, v87
	v_cndmask_b32_e64 v108, 0, v108, s[36:37]
	v_cndmask_b32_e64 v109, 0, v109, s[36:37]
	v_cndmask_b32_e64 v110, 0, v110, s[36:37]
	v_cndmask_b32_e64 v111, 0, v111, s[36:37]
	global_store_dwordx4 v[68:69], v[108:111], off
	v_lshl_add_u64 v[68:69], v[68:69], 0, s[38:39]
	v_sub_u32_e32 v65, 12, v62
	v_max_i32_e32 v65, 0, v65
	v_lshl_add_u32 v66, v65, 10, v64
	ds_read_b128 v[72:75], v66
	ds_read_b128 v[76:79], v66 offset:16
	ds_read_b128 v[80:83], v66 offset:512
	ds_read_b128 v[84:87], v66 offset:528
	s_waitcnt lgkmcnt(4)
	v_cmp_ge_u32_e64 s[36:37], 11, v62
	v_cvt_pk_bf16_f32 v104, v88, v89
	v_cvt_pk_bf16_f32 v105, v90, v91
	v_cvt_pk_bf16_f32 v106, v92, v93
	v_cvt_pk_bf16_f32 v107, v94, v95
	v_cndmask_b32_e64 v104, 0, v104, s[36:37]
	v_cndmask_b32_e64 v105, 0, v105, s[36:37]
	v_cndmask_b32_e64 v106, 0, v106, s[36:37]
	v_cndmask_b32_e64 v107, 0, v107, s[36:37]
	global_store_dwordx4 v[68:69], v[104:107], off
	v_lshl_add_u64 v[68:69], v[68:69], 0, s[38:39]
	v_cvt_pk_bf16_f32 v108, v96, v97
	v_cvt_pk_bf16_f32 v109, v98, v99
	v_cvt_pk_bf16_f32 v110, v100, v101
	v_cvt_pk_bf16_f32 v111, v102, v103
	v_cndmask_b32_e64 v108, 0, v108, s[36:37]
	v_cndmask_b32_e64 v109, 0, v109, s[36:37]
	v_cndmask_b32_e64 v110, 0, v110, s[36:37]
	v_cndmask_b32_e64 v111, 0, v111, s[36:37]
	global_store_dwordx4 v[68:69], v[108:111], off
	v_lshl_add_u64 v[68:69], v[68:69], 0, s[38:39]
	v_sub_u32_e32 v65, 13, v62
	v_max_i32_e32 v65, 0, v65
	v_lshl_add_u32 v66, v65, 10, v64
	ds_read_b128 v[88:91], v66
	ds_read_b128 v[92:95], v66 offset:16
	ds_read_b128 v[96:99], v66 offset:512
	ds_read_b128 v[100:103], v66 offset:528
	s_waitcnt lgkmcnt(4)
	v_cmp_ge_u32_e64 s[36:37], 12, v62
	v_cvt_pk_bf16_f32 v104, v72, v73
	v_cvt_pk_bf16_f32 v105, v74, v75
	v_cvt_pk_bf16_f32 v106, v76, v77
	v_cvt_pk_bf16_f32 v107, v78, v79
	v_cndmask_b32_e64 v104, 0, v104, s[36:37]
	v_cndmask_b32_e64 v105, 0, v105, s[36:37]
	v_cndmask_b32_e64 v106, 0, v106, s[36:37]
	v_cndmask_b32_e64 v107, 0, v107, s[36:37]
	global_store_dwordx4 v[68:69], v[104:107], off
	v_lshl_add_u64 v[68:69], v[68:69], 0, s[38:39]
	v_cvt_pk_bf16_f32 v108, v80, v81
	v_cvt_pk_bf16_f32 v109, v82, v83
	v_cvt_pk_bf16_f32 v110, v84, v85
	v_cvt_pk_bf16_f32 v111, v86, v87
	v_cndmask_b32_e64 v108, 0, v108, s[36:37]
	v_cndmask_b32_e64 v109, 0, v109, s[36:37]
	v_cndmask_b32_e64 v110, 0, v110, s[36:37]
	v_cndmask_b32_e64 v111, 0, v111, s[36:37]
	global_store_dwordx4 v[68:69], v[108:111], off
	v_lshl_add_u64 v[68:69], v[68:69], 0, s[38:39]
	v_sub_u32_e32 v65, 14, v62
	v_max_i32_e32 v65, 0, v65
	v_lshl_add_u32 v66, v65, 10, v64
	ds_read_b128 v[72:75], v66
	ds_read_b128 v[76:79], v66 offset:16
	ds_read_b128 v[80:83], v66 offset:512
	ds_read_b128 v[84:87], v66 offset:528
	s_waitcnt lgkmcnt(4)
; DI u32x4 pack8(const float* f) { u32x4 w; w.x = pk2(f[0], f[1]); w.y = pk2(f[2], f[3]); w.z = pk2(f[4], f[5]); w.w = pk2(f[6], f[7]); return w; }
; DI void phase_s5pre(LAS unsigned char* lds, PP p, int l, int bid, int nblk) {
;     ...
;         for (int id = tid; id < 512 * 80; id += NTHR) { const int n = id / 80, oc = id % 80, t = n >> 4, ho = n & 15; float f[8];
;             if (oc < 64) { const int s = oc >> 1, hi0 = (oc & 1) * 8;
;                 for (int i = 0; i < 8; ++i) f[i] = (s <= t) ? kt[(t - s) * 256 + ho * 16 + hi0 + i] : 0.f;
;             } else { for (int i = 0; i < 8; ++i) { const int cc = (oc - 64) * 8 + i, ri = cc >> 6, pp = cc & 63;
;                 const float ar = apr[(t + 1) * 64 + pp], ai = api[(t + 1) * 64 + pp], cr = ccr[ho * 64 + pp], ci = cci[ho * 64 + pp];
;                 f[i] = ri == 0 ? (cr * ar - ci * ai) : -(cr * ai + ci * ar); } }
;             *(u32x4*)(bt2 + ((size_t)g * 512 + n) * 640 + oc * 8) = pack8(f); }
	v_cmp_ge_u32_e64 s[36:37], 13, v62
	v_cvt_pk_bf16_f32 v104, v88, v89
	v_cvt_pk_bf16_f32 v105, v90, v91
	v_cvt_pk_bf16_f32 v106, v92, v93
	v_cvt_pk_bf16_f32 v107, v94, v95
	v_cndmask_b32_e64 v104, 0, v104, s[36:37]
	v_cndmask_b32_e64 v105, 0, v105, s[36:37]
	v_cndmask_b32_e64 v106, 0, v106, s[36:37]
	v_cndmask_b32_e64 v107, 0, v107, s[36:37]
	global_store_dwordx4 v[68:69], v[104:107], off
	v_lshl_add_u64 v[68:69], v[68:69], 0, s[38:39]
	v_cvt_pk_bf16_f32 v108, v96, v97
	v_cvt_pk_bf16_f32 v109, v98, v99
	v_cvt_pk_bf16_f32 v110, v100, v101
	v_cvt_pk_bf16_f32 v111, v102, v103
	v_cndmask_b32_e64 v108, 0, v108, s[36:37]
	v_cndmask_b32_e64 v109, 0, v109, s[36:37]
	v_cndmask_b32_e64 v110, 0, v110, s[36:37]
	v_cndmask_b32_e64 v111, 0, v111, s[36:37]
	global_store_dwordx4 v[68:69], v[108:111], off
	v_lshl_add_u64 v[68:69], v[68:69], 0, s[38:39]
	v_sub_u32_e32 v65, 15, v62
	v_max_i32_e32 v65, 0, v65
	v_lshl_add_u32 v66, v65, 10, v64
	ds_read_b128 v[88:91], v66
	ds_read_b128 v[92:95], v66 offset:16
	ds_read_b128 v[96:99], v66 offset:512
	ds_read_b128 v[100:103], v66 offset:528
	s_waitcnt lgkmcnt(4)
	v_cmp_ge_u32_e64 s[36:37], 14, v62
	v_cvt_pk_bf16_f32 v104, v72, v73
	v_cvt_pk_bf16_f32 v105, v74, v75
	v_cvt_pk_bf16_f32 v106, v76, v77
	v_cvt_pk_bf16_f32 v107, v78, v79
	v_cndmask_b32_e64 v104, 0, v104, s[36:37]
	v_cndmask_b32_e64 v105, 0, v105, s[36:37]
	v_cndmask_b32_e64 v106, 0, v106, s[36:37]
	v_cndmask_b32_e64 v107, 0, v107, s[36:37]
	global_store_dwordx4 v[68:69], v[104:107], off
	v_lshl_add_u64 v[68:69], v[68:69], 0, s[38:39]
	v_cvt_pk_bf16_f32 v108, v80, v81
	v_cvt_pk_bf16_f32 v109, v82, v83
	v_cvt_pk_bf16_f32 v110, v84, v85
	v_cvt_pk_bf16_f32 v111, v86, v87
	v_cndmask_b32_e64 v108, 0, v108, s[36:37]
	v_cndmask_b32_e64 v109, 0, v109, s[36:37]
	v_cndmask_b32_e64 v110, 0, v110, s[36:37]
	v_cndmask_b32_e64 v111, 0, v111, s[36:37]
	global_store_dwordx4 v[68:69], v[108:111], off
	v_lshl_add_u64 v[68:69], v[68:69], 0, s[38:39]
	v_sub_u32_e32 v65, 16, v62
	v_max_i32_e32 v65, 0, v65
	v_lshl_add_u32 v66, v65, 10, v64
	ds_read_b128 v[72:75], v66
	ds_read_b128 v[76:79], v66 offset:16
	ds_read_b128 v[80:83], v66 offset:512
	ds_read_b128 v[84:87], v66 offset:528
	s_waitcnt lgkmcnt(4)
	v_cmp_ge_u32_e64 s[36:37], 15, v62
	v_cvt_pk_bf16_f32 v104, v88, v89
	v_cvt_pk_bf16_f32 v105, v90, v91
	v_cvt_pk_bf16_f32 v106, v92, v93
	v_cvt_pk_bf16_f32 v107, v94, v95
	v_cndmask_b32_e64 v104, 0, v104, s[36:37]
	v_cndmask_b32_e64 v105, 0, v105, s[36:37]
	v_cndmask_b32_e64 v106, 0, v106, s[36:37]
	v_cndmask_b32_e64 v107, 0, v107, s[36:37]
	global_store_dwordx4 v[68:69], v[104:107], off
	v_lshl_add_u64 v[68:69], v[68:69], 0, s[38:39]
	v_cvt_pk_bf16_f32 v108, v96, v97
	v_cvt_pk_bf16_f32 v109, v98, v99
	v_cvt_pk_bf16_f32 v110, v100, v101
	v_cvt_pk_bf16_f32 v111, v102, v103
	v_cndmask_b32_e64 v108, 0, v108, s[36:37]
	v_cndmask_b32_e64 v109, 0, v109, s[36:37]
	v_cndmask_b32_e64 v110, 0, v110, s[36:37]
	v_cndmask_b32_e64 v111, 0, v111, s[36:37]
	global_store_dwordx4 v[68:69], v[108:111], off
	v_lshl_add_u64 v[68:69], v[68:69], 0, s[38:39]
	v_sub_u32_e32 v65, 17, v62
	v_max_i32_e32 v65, 0, v65
	v_lshl_add_u32 v66, v65, 10, v64
	ds_read_b128 v[88:91], v66
	ds_read_b128 v[92:95], v66 offset:16
	ds_read_b128 v[96:99], v66 offset:512
	ds_read_b128 v[100:103], v66 offset:528
	s_waitcnt lgkmcnt(4)
	v_cmp_ge_u32_e64 s[36:37], 16, v62
	v_cvt_pk_bf16_f32 v104, v72, v73
	v_cvt_pk_bf16_f32 v105, v74, v75
	v_cvt_pk_bf16_f32 v106, v76, v77
	v_cvt_pk_bf16_f32 v107, v78, v79
	v_cndmask_b32_e64 v104, 0, v104, s[36:37]
	v_cndmask_b32_e64 v105, 0, v105, s[36:37]
	v_cndmask_b32_e64 v106, 0, v106, s[36:37]
	v_cndmask_b32_e64 v107, 0, v107, s[36:37]
	global_store_dwordx4 v[68:69], v[104:107], off
	v_lshl_add_u64 v[68:69], v[68:69], 0, s[38:39]
	v_cvt_pk_bf16_f32 v108, v80, v81
	v_cvt_pk_bf16_f32 v109, v82, v83
	v_cvt_pk_bf16_f32 v110, v84, v85
	v_cvt_pk_bf16_f32 v111, v86, v87
	v_cndmask_b32_e64 v108, 0, v108, s[36:37]
	v_cndmask_b32_e64 v109, 0, v109, s[36:37]
	v_cndmask_b32_e64 v110, 0, v110, s[36:37]
	v_cndmask_b32_e64 v111, 0, v111, s[36:37]
	global_store_dwordx4 v[68:69], v[108:111], off
	v_lshl_add_u64 v[68:69], v[68:69], 0, s[38:39]
	v_sub_u32_e32 v65, 18, v62
	v_max_i32_e32 v65, 0, v65
	v_lshl_add_u32 v66, v65, 10, v64
	ds_read_b128 v[72:75], v66
	ds_read_b128 v[76:79], v66 offset:16
	ds_read_b128 v[80:83], v66 offset:512
	ds_read_b128 v[84:87], v66 offset:528
	s_waitcnt lgkmcnt(4)
	v_cmp_ge_u32_e64 s[36:37], 17, v62
	v_cvt_pk_bf16_f32 v104, v88, v89
	v_cvt_pk_bf16_f32 v105, v90, v91
	v_cvt_pk_bf16_f32 v106, v92, v93
	v_cvt_pk_bf16_f32 v107, v94, v95
	v_cndmask_b32_e64 v104, 0, v104, s[36:37]
	v_cndmask_b32_e64 v105, 0, v105, s[36:37]
	v_cndmask_b32_e64 v106, 0, v106, s[36:37]
	v_cndmask_b32_e64 v107, 0, v107, s[36:37]
	global_store_dwordx4 v[68:69], v[104:107], off
	v_lshl_add_u64 v[68:69], v[68:69], 0, s[38:39]
	v_cvt_pk_bf16_f32 v108, v96, v97
	v_cvt_pk_bf16_f32 v109, v98, v99
	v_cvt_pk_bf16_f32 v110, v100, v101
	v_cvt_pk_bf16_f32 v111, v102, v103
	v_cndmask_b32_e64 v108, 0, v108, s[36:37]
	v_cndmask_b32_e64 v109, 0, v109, s[36:37]
	v_cndmask_b32_e64 v110, 0, v110, s[36:37]
	v_cndmask_b32_e64 v111, 0, v111, s[36:37]
	global_store_dwordx4 v[68:69], v[108:111], off
	v_lshl_add_u64 v[68:69], v[68:69], 0, s[38:39]
	v_sub_u32_e32 v65, 19, v62
	v_max_i32_e32 v65, 0, v65
	v_lshl_add_u32 v66, v65, 10, v64
	ds_read_b128 v[88:91], v66
	ds_read_b128 v[92:95], v66 offset:16
	ds_read_b128 v[96:99], v66 offset:512
	ds_read_b128 v[100:103], v66 offset:528
	s_waitcnt lgkmcnt(4)
; DI u32x4 pack8(const float* f) { u32x4 w; w.x = pk2(f[0], f[1]); w.y = pk2(f[2], f[3]); w.z = pk2(f[4], f[5]); w.w = pk2(f[6], f[7]); return w; }
; DI void phase_s5pre(LAS unsigned char* lds, PP p, int l, int bid, int nblk) {
;     ...
;         for (int id = tid; id < 512 * 80; id += NTHR) { const int n = id / 80, oc = id % 80, t = n >> 4, ho = n & 15; float f[8];
;             if (oc < 64) { const int s = oc >> 1, hi0 = (oc & 1) * 8;
;                 for (int i = 0; i < 8; ++i) f[i] = (s <= t) ? kt[(t - s) * 256 + ho * 16 + hi0 + i] : 0.f;
;             } else { for (int i = 0; i < 8; ++i) { const int cc = (oc - 64) * 8 + i, ri = cc >> 6, pp = cc & 63;
;                 const float ar = apr[(t + 1) * 64 + pp], ai = api[(t + 1) * 64 + pp], cr = ccr[ho * 64 + pp], ci = cci[ho * 64 + pp];
;                 f[i] = ri == 0 ? (cr * ar - ci * ai) : -(cr * ai + ci * ar); } }
;             *(u32x4*)(bt2 + ((size_t)g * 512 + n) * 640 + oc * 8) = pack8(f); }
	v_cmp_ge_u32_e64 s[36:37], 18, v62
	v_cvt_pk_bf16_f32 v104, v72, v73
	v_cvt_pk_bf16_f32 v105, v74, v75
	v_cvt_pk_bf16_f32 v106, v76, v77
	v_cvt_pk_bf16_f32 v107, v78, v79
	v_cndmask_b32_e64 v104, 0, v104, s[36:37]
	v_cndmask_b32_e64 v105, 0, v105, s[36:37]
	v_cndmask_b32_e64 v106, 0, v106, s[36:37]
	v_cndmask_b32_e64 v107, 0, v107, s[36:37]
	global_store_dwordx4 v[68:69], v[104:107], off
	v_lshl_add_u64 v[68:69], v[68:69], 0, s[38:39]
	v_cvt_pk_bf16_f32 v108, v80, v81
	v_cvt_pk_bf16_f32 v109, v82, v83
	v_cvt_pk_bf16_f32 v110, v84, v85
	v_cvt_pk_bf16_f32 v111, v86, v87
	v_cndmask_b32_e64 v108, 0, v108, s[36:37]
	v_cndmask_b32_e64 v109, 0, v109, s[36:37]
	v_cndmask_b32_e64 v110, 0, v110, s[36:37]
	v_cndmask_b32_e64 v111, 0, v111, s[36:37]
	global_store_dwordx4 v[68:69], v[108:111], off
	v_lshl_add_u64 v[68:69], v[68:69], 0, s[38:39]
	v_sub_u32_e32 v65, 20, v62
	v_max_i32_e32 v65, 0, v65
	v_lshl_add_u32 v66, v65, 10, v64
	ds_read_b128 v[72:75], v66
	ds_read_b128 v[76:79], v66 offset:16
	ds_read_b128 v[80:83], v66 offset:512
	ds_read_b128 v[84:87], v66 offset:528
	s_waitcnt lgkmcnt(4)
	v_cmp_ge_u32_e64 s[36:37], 19, v62
	v_cvt_pk_bf16_f32 v104, v88, v89
	v_cvt_pk_bf16_f32 v105, v90, v91
	v_cvt_pk_bf16_f32 v106, v92, v93
	v_cvt_pk_bf16_f32 v107, v94, v95
	v_cndmask_b32_e64 v104, 0, v104, s[36:37]
	v_cndmask_b32_e64 v105, 0, v105, s[36:37]
	v_cndmask_b32_e64 v106, 0, v106, s[36:37]
	v_cndmask_b32_e64 v107, 0, v107, s[36:37]
	global_store_dwordx4 v[68:69], v[104:107], off
	v_lshl_add_u64 v[68:69], v[68:69], 0, s[38:39]
	v_cvt_pk_bf16_f32 v108, v96, v97
	v_cvt_pk_bf16_f32 v109, v98, v99
	v_cvt_pk_bf16_f32 v110, v100, v101
	v_cvt_pk_bf16_f32 v111, v102, v103
	v_cndmask_b32_e64 v108, 0, v108, s[36:37]
	v_cndmask_b32_e64 v109, 0, v109, s[36:37]
	v_cndmask_b32_e64 v110, 0, v110, s[36:37]
	v_cndmask_b32_e64 v111, 0, v111, s[36:37]
	global_store_dwordx4 v[68:69], v[108:111], off
	v_lshl_add_u64 v[68:69], v[68:69], 0, s[38:39]
	v_sub_u32_e32 v65, 21, v62
	v_max_i32_e32 v65, 0, v65
	v_lshl_add_u32 v66, v65, 10, v64
	ds_read_b128 v[88:91], v66
	ds_read_b128 v[92:95], v66 offset:16
	ds_read_b128 v[96:99], v66 offset:512
	ds_read_b128 v[100:103], v66 offset:528
	s_waitcnt lgkmcnt(4)
	v_cmp_ge_u32_e64 s[36:37], 20, v62
	v_cvt_pk_bf16_f32 v104, v72, v73
	v_cvt_pk_bf16_f32 v105, v74, v75
	v_cvt_pk_bf16_f32 v106, v76, v77
	v_cvt_pk_bf16_f32 v107, v78, v79
	v_cndmask_b32_e64 v104, 0, v104, s[36:37]
	v_cndmask_b32_e64 v105, 0, v105, s[36:37]
	v_cndmask_b32_e64 v106, 0, v106, s[36:37]
	v_cndmask_b32_e64 v107, 0, v107, s[36:37]
	global_store_dwordx4 v[68:69], v[104:107], off
	v_lshl_add_u64 v[68:69], v[68:69], 0, s[38:39]
	v_cvt_pk_bf16_f32 v108, v80, v81
	v_cvt_pk_bf16_f32 v109, v82, v83
	v_cvt_pk_bf16_f32 v110, v84, v85
	v_cvt_pk_bf16_f32 v111, v86, v87
	v_cndmask_b32_e64 v108, 0, v108, s[36:37]
	v_cndmask_b32_e64 v109, 0, v109, s[36:37]
	v_cndmask_b32_e64 v110, 0, v110, s[36:37]
	v_cndmask_b32_e64 v111, 0, v111, s[36:37]
	global_store_dwordx4 v[68:69], v[108:111], off
	v_lshl_add_u64 v[68:69], v[68:69], 0, s[38:39]
	v_sub_u32_e32 v65, 22, v62
	v_max_i32_e32 v65, 0, v65
	v_lshl_add_u32 v66, v65, 10, v64
	ds_read_b128 v[72:75], v66
	ds_read_b128 v[76:79], v66 offset:16
	ds_read_b128 v[80:83], v66 offset:512
	ds_read_b128 v[84:87], v66 offset:528
	s_waitcnt lgkmcnt(4)
	v_cmp_ge_u32_e64 s[36:37], 21, v62
	v_cvt_pk_bf16_f32 v104, v88, v89
	v_cvt_pk_bf16_f32 v105, v90, v91
	v_cvt_pk_bf16_f32 v106, v92, v93
	v_cvt_pk_bf16_f32 v107, v94, v95
	v_cndmask_b32_e64 v104, 0, v104, s[36:37]
	v_cndmask_b32_e64 v105, 0, v105, s[36:37]
	v_cndmask_b32_e64 v106, 0, v106, s[36:37]
	v_cndmask_b32_e64 v107, 0, v107, s[36:37]
	global_store_dwordx4 v[68:69], v[104:107], off
	v_lshl_add_u64 v[68:69], v[68:69], 0, s[38:39]
	v_cvt_pk_bf16_f32 v108, v96, v97
	v_cvt_pk_bf16_f32 v109, v98, v99
	v_cvt_pk_bf16_f32 v110, v100, v101
	v_cvt_pk_bf16_f32 v111, v102, v103
	v_cndmask_b32_e64 v108, 0, v108, s[36:37]
	v_cndmask_b32_e64 v109, 0, v109, s[36:37]
	v_cndmask_b32_e64 v110, 0, v110, s[36:37]
	v_cndmask_b32_e64 v111, 0, v111, s[36:37]
	global_store_dwordx4 v[68:69], v[108:111], off
	v_lshl_add_u64 v[68:69], v[68:69], 0, s[38:39]
	v_sub_u32_e32 v65, 23, v62
	v_max_i32_e32 v65, 0, v65
	v_lshl_add_u32 v66, v65, 10, v64
	ds_read_b128 v[88:91], v66
	ds_read_b128 v[92:95], v66 offset:16
	ds_read_b128 v[96:99], v66 offset:512
	ds_read_b128 v[100:103], v66 offset:528
	s_waitcnt lgkmcnt(4)
	v_cmp_ge_u32_e64 s[36:37], 22, v62
	v_cvt_pk_bf16_f32 v104, v72, v73
	v_cvt_pk_bf16_f32 v105, v74, v75
	v_cvt_pk_bf16_f32 v106, v76, v77
	v_cvt_pk_bf16_f32 v107, v78, v79
	v_cndmask_b32_e64 v104, 0, v104, s[36:37]
	v_cndmask_b32_e64 v105, 0, v105, s[36:37]
	v_cndmask_b32_e64 v106, 0, v106, s[36:37]
	v_cndmask_b32_e64 v107, 0, v107, s[36:37]
	global_store_dwordx4 v[68:69], v[104:107], off
	v_lshl_add_u64 v[68:69], v[68:69], 0, s[38:39]
	v_cvt_pk_bf16_f32 v108, v80, v81
	v_cvt_pk_bf16_f32 v109, v82, v83
	v_cvt_pk_bf16_f32 v110, v84, v85
	v_cvt_pk_bf16_f32 v111, v86, v87
	v_cndmask_b32_e64 v108, 0, v108, s[36:37]
	v_cndmask_b32_e64 v109, 0, v109, s[36:37]
	v_cndmask_b32_e64 v110, 0, v110, s[36:37]
	v_cndmask_b32_e64 v111, 0, v111, s[36:37]
	global_store_dwordx4 v[68:69], v[108:111], off
	v_lshl_add_u64 v[68:69], v[68:69], 0, s[38:39]
	v_sub_u32_e32 v65, 24, v62
	v_max_i32_e32 v65, 0, v65
	v_lshl_add_u32 v66, v65, 10, v64
	ds_read_b128 v[72:75], v66
	ds_read_b128 v[76:79], v66 offset:16
	ds_read_b128 v[80:83], v66 offset:512
	ds_read_b128 v[84:87], v66 offset:528
	s_waitcnt lgkmcnt(4)
; DI u32x4 pack8(const float* f) { u32x4 w; w.x = pk2(f[0], f[1]); w.y = pk2(f[2], f[3]); w.z = pk2(f[4], f[5]); w.w = pk2(f[6], f[7]); return w; }
; DI void phase_s5pre(LAS unsigned char* lds, PP p, int l, int bid, int nblk) {
;     ...
;         for (int id = tid; id < 512 * 80; id += NTHR) { const int n = id / 80, oc = id % 80, t = n >> 4, ho = n & 15; float f[8];
;             if (oc < 64) { const int s = oc >> 1, hi0 = (oc & 1) * 8;
;                 for (int i = 0; i < 8; ++i) f[i] = (s <= t) ? kt[(t - s) * 256 + ho * 16 + hi0 + i] : 0.f;
;             } else { for (int i = 0; i < 8; ++i) { const int cc = (oc - 64) * 8 + i, ri = cc >> 6, pp = cc & 63;
;                 const float ar = apr[(t + 1) * 64 + pp], ai = api[(t + 1) * 64 + pp], cr = ccr[ho * 64 + pp], ci = cci[ho * 64 + pp];
;                 f[i] = ri == 0 ? (cr * ar - ci * ai) : -(cr * ai + ci * ar); } }
;             *(u32x4*)(bt2 + ((size_t)g * 512 + n) * 640 + oc * 8) = pack8(f); }
	v_cmp_ge_u32_e64 s[36:37], 23, v62
	v_cvt_pk_bf16_f32 v104, v88, v89
	v_cvt_pk_bf16_f32 v105, v90, v91
	v_cvt_pk_bf16_f32 v106, v92, v93
	v_cvt_pk_bf16_f32 v107, v94, v95
	v_cndmask_b32_e64 v104, 0, v104, s[36:37]
	v_cndmask_b32_e64 v105, 0, v105, s[36:37]
	v_cndmask_b32_e64 v106, 0, v106, s[36:37]
	v_cndmask_b32_e64 v107, 0, v107, s[36:37]
	global_store_dwordx4 v[68:69], v[104:107], off
	v_lshl_add_u64 v[68:69], v[68:69], 0, s[38:39]
	v_cvt_pk_bf16_f32 v108, v96, v97
	v_cvt_pk_bf16_f32 v109, v98, v99
	v_cvt_pk_bf16_f32 v110, v100, v101
	v_cvt_pk_bf16_f32 v111, v102, v103
	v_cndmask_b32_e64 v108, 0, v108, s[36:37]
	v_cndmask_b32_e64 v109, 0, v109, s[36:37]
	v_cndmask_b32_e64 v110, 0, v110, s[36:37]
	v_cndmask_b32_e64 v111, 0, v111, s[36:37]
	global_store_dwordx4 v[68:69], v[108:111], off
	v_lshl_add_u64 v[68:69], v[68:69], 0, s[38:39]
	v_sub_u32_e32 v65, 25, v62
	v_max_i32_e32 v65, 0, v65
	v_lshl_add_u32 v66, v65, 10, v64
	ds_read_b128 v[88:91], v66
	ds_read_b128 v[92:95], v66 offset:16
	ds_read_b128 v[96:99], v66 offset:512
	ds_read_b128 v[100:103], v66 offset:528
	s_waitcnt lgkmcnt(4)
	v_cmp_ge_u32_e64 s[36:37], 24, v62
	v_cvt_pk_bf16_f32 v104, v72, v73
	v_cvt_pk_bf16_f32 v105, v74, v75
	v_cvt_pk_bf16_f32 v106, v76, v77
	v_cvt_pk_bf16_f32 v107, v78, v79
	v_cndmask_b32_e64 v104, 0, v104, s[36:37]
	v_cndmask_b32_e64 v105, 0, v105, s[36:37]
	v_cndmask_b32_e64 v106, 0, v106, s[36:37]
	v_cndmask_b32_e64 v107, 0, v107, s[36:37]
	global_store_dwordx4 v[68:69], v[104:107], off
	v_lshl_add_u64 v[68:69], v[68:69], 0, s[38:39]
	v_cvt_pk_bf16_f32 v108, v80, v81
	v_cvt_pk_bf16_f32 v109, v82, v83
	v_cvt_pk_bf16_f32 v110, v84, v85
	v_cvt_pk_bf16_f32 v111, v86, v87
	v_cndmask_b32_e64 v108, 0, v108, s[36:37]
	v_cndmask_b32_e64 v109, 0, v109, s[36:37]
	v_cndmask_b32_e64 v110, 0, v110, s[36:37]
	v_cndmask_b32_e64 v111, 0, v111, s[36:37]
	global_store_dwordx4 v[68:69], v[108:111], off
	v_lshl_add_u64 v[68:69], v[68:69], 0, s[38:39]
	v_sub_u32_e32 v65, 26, v62
	v_max_i32_e32 v65, 0, v65
	v_lshl_add_u32 v66, v65, 10, v64
	ds_read_b128 v[72:75], v66
	ds_read_b128 v[76:79], v66 offset:16
	ds_read_b128 v[80:83], v66 offset:512
	ds_read_b128 v[84:87], v66 offset:528
	s_waitcnt lgkmcnt(4)
	v_cmp_ge_u32_e64 s[36:37], 25, v62
	v_cvt_pk_bf16_f32 v104, v88, v89
	v_cvt_pk_bf16_f32 v105, v90, v91
	v_cvt_pk_bf16_f32 v106, v92, v93
	v_cvt_pk_bf16_f32 v107, v94, v95
	v_cndmask_b32_e64 v104, 0, v104, s[36:37]
	v_cndmask_b32_e64 v105, 0, v105, s[36:37]
	v_cndmask_b32_e64 v106, 0, v106, s[36:37]
	v_cndmask_b32_e64 v107, 0, v107, s[36:37]
	global_store_dwordx4 v[68:69], v[104:107], off
	v_lshl_add_u64 v[68:69], v[68:69], 0, s[38:39]
	v_cvt_pk_bf16_f32 v108, v96, v97
	v_cvt_pk_bf16_f32 v109, v98, v99
	v_cvt_pk_bf16_f32 v110, v100, v101
	v_cvt_pk_bf16_f32 v111, v102, v103
	v_cndmask_b32_e64 v108, 0, v108, s[36:37]
	v_cndmask_b32_e64 v109, 0, v109, s[36:37]
	v_cndmask_b32_e64 v110, 0, v110, s[36:37]
	v_cndmask_b32_e64 v111, 0, v111, s[36:37]
	global_store_dwordx4 v[68:69], v[108:111], off
	v_lshl_add_u64 v[68:69], v[68:69], 0, s[38:39]
	v_sub_u32_e32 v65, 27, v62
	v_max_i32_e32 v65, 0, v65
	v_lshl_add_u32 v66, v65, 10, v64
	ds_read_b128 v[88:91], v66
	ds_read_b128 v[92:95], v66 offset:16
	ds_read_b128 v[96:99], v66 offset:512
	ds_read_b128 v[100:103], v66 offset:528
	s_waitcnt lgkmcnt(4)
	v_cmp_ge_u32_e64 s[36:37], 26, v62
	v_cvt_pk_bf16_f32 v104, v72, v73
	v_cvt_pk_bf16_f32 v105, v74, v75
	v_cvt_pk_bf16_f32 v106, v76, v77
	v_cvt_pk_bf16_f32 v107, v78, v79
	v_cndmask_b32_e64 v104, 0, v104, s[36:37]
	v_cndmask_b32_e64 v105, 0, v105, s[36:37]
	v_cndmask_b32_e64 v106, 0, v106, s[36:37]
	v_cndmask_b32_e64 v107, 0, v107, s[36:37]
	global_store_dwordx4 v[68:69], v[104:107], off
	v_lshl_add_u64 v[68:69], v[68:69], 0, s[38:39]
	v_cvt_pk_bf16_f32 v108, v80, v81
	v_cvt_pk_bf16_f32 v109, v82, v83
	v_cvt_pk_bf16_f32 v110, v84, v85
	v_cvt_pk_bf16_f32 v111, v86, v87
	v_cndmask_b32_e64 v108, 0, v108, s[36:37]
	v_cndmask_b32_e64 v109, 0, v109, s[36:37]
	v_cndmask_b32_e64 v110, 0, v110, s[36:37]
	v_cndmask_b32_e64 v111, 0, v111, s[36:37]
	global_store_dwordx4 v[68:69], v[108:111], off
	v_lshl_add_u64 v[68:69], v[68:69], 0, s[38:39]
	v_sub_u32_e32 v65, 28, v62
	v_max_i32_e32 v65, 0, v65
	v_lshl_add_u32 v66, v65, 10, v64
	ds_read_b128 v[72:75], v66
	ds_read_b128 v[76:79], v66 offset:16
	ds_read_b128 v[80:83], v66 offset:512
	ds_read_b128 v[84:87], v66 offset:528
	s_waitcnt lgkmcnt(4)
	v_cmp_ge_u32_e64 s[36:37], 27, v62
	v_cvt_pk_bf16_f32 v104, v88, v89
	v_cvt_pk_bf16_f32 v105, v90, v91
	v_cvt_pk_bf16_f32 v106, v92, v93
	v_cvt_pk_bf16_f32 v107, v94, v95
	v_cndmask_b32_e64 v104, 0, v104, s[36:37]
	v_cndmask_b32_e64 v105, 0, v105, s[36:37]
	v_cndmask_b32_e64 v106, 0, v106, s[36:37]
	v_cndmask_b32_e64 v107, 0, v107, s[36:37]
	global_store_dwordx4 v[68:69], v[104:107], off
	v_lshl_add_u64 v[68:69], v[68:69], 0, s[38:39]
	v_cvt_pk_bf16_f32 v108, v96, v97
	v_cvt_pk_bf16_f32 v109, v98, v99
	v_cvt_pk_bf16_f32 v110, v100, v101
	v_cvt_pk_bf16_f32 v111, v102, v103
	v_cndmask_b32_e64 v108, 0, v108, s[36:37]
	v_cndmask_b32_e64 v109, 0, v109, s[36:37]
	v_cndmask_b32_e64 v110, 0, v110, s[36:37]
	v_cndmask_b32_e64 v111, 0, v111, s[36:37]
	global_store_dwordx4 v[68:69], v[108:111], off
	v_lshl_add_u64 v[68:69], v[68:69], 0, s[38:39]
	v_sub_u32_e32 v65, 29, v62
	v_max_i32_e32 v65, 0, v65
	v_lshl_add_u32 v66, v65, 10, v64
	ds_read_b128 v[88:91], v66
	ds_read_b128 v[92:95], v66 offset:16
	ds_read_b128 v[96:99], v66 offset:512
	ds_read_b128 v[100:103], v66 offset:528
	s_waitcnt lgkmcnt(4)
; DI u32x4 pack8(const float* f) { u32x4 w; w.x = pk2(f[0], f[1]); w.y = pk2(f[2], f[3]); w.z = pk2(f[4], f[5]); w.w = pk2(f[6], f[7]); return w; }
; DI void phase_s5pre(LAS unsigned char* lds, PP p, int l, int bid, int nblk) {
;     ...
;         for (int id = tid; id < 512 * 80; id += NTHR) { const int n = id / 80, oc = id % 80, t = n >> 4, ho = n & 15; float f[8];
;             if (oc < 64) { const int s = oc >> 1, hi0 = (oc & 1) * 8;
;                 for (int i = 0; i < 8; ++i) f[i] = (s <= t) ? kt[(t - s) * 256 + ho * 16 + hi0 + i] : 0.f;
;             } else { for (int i = 0; i < 8; ++i) { const int cc = (oc - 64) * 8 + i, ri = cc >> 6, pp = cc & 63;
;                 const float ar = apr[(t + 1) * 64 + pp], ai = api[(t + 1) * 64 + pp], cr = ccr[ho * 64 + pp], ci = cci[ho * 64 + pp];
;                 f[i] = ri == 0 ? (cr * ar - ci * ai) : -(cr * ai + ci * ar); } }
;             *(u32x4*)(bt2 + ((size_t)g * 512 + n) * 640 + oc * 8) = pack8(f); }
	v_cmp_ge_u32_e64 s[36:37], 28, v62
	v_cvt_pk_bf16_f32 v104, v72, v73
	v_cvt_pk_bf16_f32 v105, v74, v75
	v_cvt_pk_bf16_f32 v106, v76, v77
	v_cvt_pk_bf16_f32 v107, v78, v79
	v_cndmask_b32_e64 v104, 0, v104, s[36:37]
	v_cndmask_b32_e64 v105, 0, v105, s[36:37]
	v_cndmask_b32_e64 v106, 0, v106, s[36:37]
	v_cndmask_b32_e64 v107, 0, v107, s[36:37]
	global_store_dwordx4 v[68:69], v[104:107], off
	v_lshl_add_u64 v[68:69], v[68:69], 0, s[38:39]
	v_cvt_pk_bf16_f32 v108, v80, v81
	v_cvt_pk_bf16_f32 v109, v82, v83
	v_cvt_pk_bf16_f32 v110, v84, v85
	v_cvt_pk_bf16_f32 v111, v86, v87
	v_cndmask_b32_e64 v108, 0, v108, s[36:37]
	v_cndmask_b32_e64 v109, 0, v109, s[36:37]
	v_cndmask_b32_e64 v110, 0, v110, s[36:37]
	v_cndmask_b32_e64 v111, 0, v111, s[36:37]
	global_store_dwordx4 v[68:69], v[108:111], off
	v_lshl_add_u64 v[68:69], v[68:69], 0, s[38:39]
	v_sub_u32_e32 v65, 30, v62
	v_max_i32_e32 v65, 0, v65
	v_lshl_add_u32 v66, v65, 10, v64
	ds_read_b128 v[72:75], v66
	ds_read_b128 v[76:79], v66 offset:16
	ds_read_b128 v[80:83], v66 offset:512
	ds_read_b128 v[84:87], v66 offset:528
	s_waitcnt lgkmcnt(4)
	v_cmp_ge_u32_e64 s[36:37], 29, v62
	v_cvt_pk_bf16_f32 v104, v88, v89
	v_cvt_pk_bf16_f32 v105, v90, v91
	v_cvt_pk_bf16_f32 v106, v92, v93
	v_cvt_pk_bf16_f32 v107, v94, v95
	v_cndmask_b32_e64 v104, 0, v104, s[36:37]
	v_cndmask_b32_e64 v105, 0, v105, s[36:37]
	v_cndmask_b32_e64 v106, 0, v106, s[36:37]
	v_cndmask_b32_e64 v107, 0, v107, s[36:37]
	global_store_dwordx4 v[68:69], v[104:107], off
	v_lshl_add_u64 v[68:69], v[68:69], 0, s[38:39]
	v_cvt_pk_bf16_f32 v108, v96, v97
	v_cvt_pk_bf16_f32 v109, v98, v99
	v_cvt_pk_bf16_f32 v110, v100, v101
	v_cvt_pk_bf16_f32 v111, v102, v103
	v_cndmask_b32_e64 v108, 0, v108, s[36:37]
	v_cndmask_b32_e64 v109, 0, v109, s[36:37]
	v_cndmask_b32_e64 v110, 0, v110, s[36:37]
	v_cndmask_b32_e64 v111, 0, v111, s[36:37]
	global_store_dwordx4 v[68:69], v[108:111], off
	v_lshl_add_u64 v[68:69], v[68:69], 0, s[38:39]
	v_sub_u32_e32 v65, 31, v62
	v_max_i32_e32 v65, 0, v65
	v_lshl_add_u32 v66, v65, 10, v64
	ds_read_b128 v[88:91], v66
	ds_read_b128 v[92:95], v66 offset:16
	ds_read_b128 v[96:99], v66 offset:512
	ds_read_b128 v[100:103], v66 offset:528
	s_waitcnt lgkmcnt(4)
	v_cmp_ge_u32_e64 s[36:37], 30, v62
	v_cvt_pk_bf16_f32 v104, v72, v73
	v_cvt_pk_bf16_f32 v105, v74, v75
	v_cvt_pk_bf16_f32 v106, v76, v77
	v_cvt_pk_bf16_f32 v107, v78, v79
	v_cndmask_b32_e64 v104, 0, v104, s[36:37]
	v_cndmask_b32_e64 v105, 0, v105, s[36:37]
	v_cndmask_b32_e64 v106, 0, v106, s[36:37]
	v_cndmask_b32_e64 v107, 0, v107, s[36:37]
	global_store_dwordx4 v[68:69], v[104:107], off
	v_lshl_add_u64 v[68:69], v[68:69], 0, s[38:39]
	v_cvt_pk_bf16_f32 v108, v80, v81
	v_cvt_pk_bf16_f32 v109, v82, v83
	v_cvt_pk_bf16_f32 v110, v84, v85
	v_cvt_pk_bf16_f32 v111, v86, v87
	v_cndmask_b32_e64 v108, 0, v108, s[36:37]
	v_cndmask_b32_e64 v109, 0, v109, s[36:37]
	v_cndmask_b32_e64 v110, 0, v110, s[36:37]
	v_cndmask_b32_e64 v111, 0, v111, s[36:37]
	global_store_dwordx4 v[68:69], v[108:111], off
	v_lshl_add_u64 v[68:69], v[68:69], 0, s[38:39]
	s_waitcnt lgkmcnt(0)
	v_cmp_ge_u32_e64 s[36:37], 31, v62
	v_cvt_pk_bf16_f32 v104, v88, v89
	v_cvt_pk_bf16_f32 v105, v90, v91
	v_cvt_pk_bf16_f32 v106, v92, v93
	v_cvt_pk_bf16_f32 v107, v94, v95
	v_cndmask_b32_e64 v104, 0, v104, s[36:37]
	v_cndmask_b32_e64 v105, 0, v105, s[36:37]
	v_cndmask_b32_e64 v106, 0, v106, s[36:37]
	v_cndmask_b32_e64 v107, 0, v107, s[36:37]
	global_store_dwordx4 v[68:69], v[104:107], off
	v_lshl_add_u64 v[68:69], v[68:69], 0, s[38:39]
	v_cvt_pk_bf16_f32 v108, v96, v97
	v_cvt_pk_bf16_f32 v109, v98, v99
	v_cvt_pk_bf16_f32 v110, v100, v101
	v_cvt_pk_bf16_f32 v111, v102, v103
	v_cndmask_b32_e64 v108, 0, v108, s[36:37]
	v_cndmask_b32_e64 v109, 0, v109, s[36:37]
	v_cndmask_b32_e64 v110, 0, v110, s[36:37]
	v_cndmask_b32_e64 v111, 0, v111, s[36:37]
	global_store_dwordx4 v[68:69], v[108:111], off
	v_lshl_add_u64 v[68:69], v[68:69], 0, s[38:39]
	ds_read_b128 v[132:135], v112 offset:0
	ds_read_b128 v[136:139], v112 offset:16
	ds_read_b128 v[140:143], v113 offset:0
	ds_read_b128 v[144:147], v113 offset:16
	s_waitcnt lgkmcnt(0)
	v_mul_f32_e32 v148, v140, v124
	v_mul_f32_e32 v149, v141, v125
	v_mul_f32_e32 v150, v142, v126
	v_mul_f32_e32 v151, v143, v127
	v_mul_f32_e32 v152, v144, v128
	v_mul_f32_e32 v153, v145, v129
	v_mul_f32_e32 v154, v146, v130
	v_mul_f32_e32 v155, v147, v131
	v_fma_f32 v156, v132, v116, -v148
	v_fma_f32 v157, v133, v117, -v149
	v_fma_f32 v158, v134, v118, -v150
	v_fma_f32 v159, v135, v119, -v151
	v_fma_f32 v160, v136, v120, -v152
	v_fma_f32 v161, v137, v121, -v153
	v_fma_f32 v162, v138, v122, -v154
	v_fma_f32 v163, v139, v123, -v155
	v_cvt_pk_bf16_f32 v164, v156, v157
	v_cvt_pk_bf16_f32 v165, v158, v159
	v_cvt_pk_bf16_f32 v166, v160, v161
	v_cvt_pk_bf16_f32 v167, v162, v163
	global_store_dwordx4 v[172:173], v[164:167], off
	v_lshl_add_u64 v[172:173], v[172:173], 0, s[40:41]
	ds_read_b128 v[132:135], v112 offset:512
	ds_read_b128 v[136:139], v112 offset:528
	ds_read_b128 v[140:143], v113 offset:512
	ds_read_b128 v[144:147], v113 offset:528
	s_waitcnt lgkmcnt(0)
	v_mul_f32_e32 v148, v140, v124
	v_mul_f32_e32 v149, v141, v125
	v_mul_f32_e32 v150, v142, v126
	v_mul_f32_e32 v151, v143, v127
	v_mul_f32_e32 v152, v144, v128
	v_mul_f32_e32 v153, v145, v129
	v_mul_f32_e32 v154, v146, v130
	v_mul_f32_e32 v155, v147, v131
	v_fma_f32 v156, v132, v116, -v148
	v_fma_f32 v157, v133, v117, -v149
	v_fma_f32 v158, v134, v118, -v150
	v_fma_f32 v159, v135, v119, -v151
	v_fma_f32 v160, v136, v120, -v152
	v_fma_f32 v161, v137, v121, -v153
	v_fma_f32 v162, v138, v122, -v154
	v_fma_f32 v163, v139, v123, -v155
	v_cvt_pk_bf16_f32 v168, v156, v157
	v_cvt_pk_bf16_f32 v169, v158, v159
	v_cvt_pk_bf16_f32 v170, v160, v161
	v_cvt_pk_bf16_f32 v171, v162, v163
	global_store_dwordx4 v[172:173], v[168:171], off
	v_lshl_add_u64 v[172:173], v[172:173], 0, s[40:41]
	ds_read_b128 v[132:135], v112 offset:1024
	ds_read_b128 v[136:139], v112 offset:1040
	ds_read_b128 v[140:143], v113 offset:1024
	ds_read_b128 v[144:147], v113 offset:1040
	s_waitcnt lgkmcnt(0)
; DI u32x4 pack8(const float* f) { u32x4 w; w.x = pk2(f[0], f[1]); w.y = pk2(f[2], f[3]); w.z = pk2(f[4], f[5]); w.w = pk2(f[6], f[7]); return w; }
; DI void phase_s5pre(LAS unsigned char* lds, PP p, int l, int bid, int nblk) {
;     ...
;             } else { for (int i = 0; i < 8; ++i) { const int cc = (oc - 64) * 8 + i, ri = cc >> 6, pp = cc & 63;
;                 const float ar = apr[(t + 1) * 64 + pp], ai = api[(t + 1) * 64 + pp], cr = ccr[ho * 64 + pp], ci = cci[ho * 64 + pp];
;                 f[i] = ri == 0 ? (cr * ar - ci * ai) : -(cr * ai + ci * ar); } }
;             *(u32x4*)(bt2 + ((size_t)g * 512 + n) * 640 + oc * 8) = pack8(f); }
	v_mul_f32_e32 v148, v140, v124
	v_mul_f32_e32 v149, v141, v125
	v_mul_f32_e32 v150, v142, v126
	v_mul_f32_e32 v151, v143, v127
	v_mul_f32_e32 v152, v144, v128
	v_mul_f32_e32 v153, v145, v129
	v_mul_f32_e32 v154, v146, v130
	v_mul_f32_e32 v155, v147, v131
	v_fma_f32 v156, v132, v116, -v148
	v_fma_f32 v157, v133, v117, -v149
	v_fma_f32 v158, v134, v118, -v150
	v_fma_f32 v159, v135, v119, -v151
	v_fma_f32 v160, v136, v120, -v152
	v_fma_f32 v161, v137, v121, -v153
	v_fma_f32 v162, v138, v122, -v154
	v_fma_f32 v163, v139, v123, -v155
	v_cvt_pk_bf16_f32 v164, v156, v157
	v_cvt_pk_bf16_f32 v165, v158, v159
	v_cvt_pk_bf16_f32 v166, v160, v161
	v_cvt_pk_bf16_f32 v167, v162, v163
	global_store_dwordx4 v[172:173], v[164:167], off
	v_lshl_add_u64 v[172:173], v[172:173], 0, s[40:41]
	ds_read_b128 v[132:135], v112 offset:1536
	ds_read_b128 v[136:139], v112 offset:1552
	ds_read_b128 v[140:143], v113 offset:1536
	ds_read_b128 v[144:147], v113 offset:1552
	s_waitcnt lgkmcnt(0)
	v_mul_f32_e32 v148, v140, v124
	v_mul_f32_e32 v149, v141, v125
	v_mul_f32_e32 v150, v142, v126
	v_mul_f32_e32 v151, v143, v127
	v_mul_f32_e32 v152, v144, v128
	v_mul_f32_e32 v153, v145, v129
	v_mul_f32_e32 v154, v146, v130
	v_mul_f32_e32 v155, v147, v131
	v_fma_f32 v156, v132, v116, -v148
	v_fma_f32 v157, v133, v117, -v149
	v_fma_f32 v158, v134, v118, -v150
	v_fma_f32 v159, v135, v119, -v151
	v_fma_f32 v160, v136, v120, -v152
	v_fma_f32 v161, v137, v121, -v153
	v_fma_f32 v162, v138, v122, -v154
	v_fma_f32 v163, v139, v123, -v155
	v_cvt_pk_bf16_f32 v168, v156, v157
	v_cvt_pk_bf16_f32 v169, v158, v159
	v_cvt_pk_bf16_f32 v170, v160, v161
	v_cvt_pk_bf16_f32 v171, v162, v163
	global_store_dwordx4 v[172:173], v[168:171], off
	v_lshl_add_u64 v[172:173], v[172:173], 0, s[40:41]
	ds_read_b128 v[132:135], v112 offset:2048
	ds_read_b128 v[136:139], v112 offset:2064
	ds_read_b128 v[140:143], v113 offset:2048
	ds_read_b128 v[144:147], v113 offset:2064
	s_waitcnt lgkmcnt(0)
	v_mul_f32_e32 v148, v140, v124
	v_mul_f32_e32 v149, v141, v125
	v_mul_f32_e32 v150, v142, v126
	v_mul_f32_e32 v151, v143, v127
	v_mul_f32_e32 v152, v144, v128
	v_mul_f32_e32 v153, v145, v129
	v_mul_f32_e32 v154, v146, v130
	v_mul_f32_e32 v155, v147, v131
	v_fma_f32 v156, v132, v116, -v148
	v_fma_f32 v157, v133, v117, -v149
	v_fma_f32 v158, v134, v118, -v150
	v_fma_f32 v159, v135, v119, -v151
	v_fma_f32 v160, v136, v120, -v152
	v_fma_f32 v161, v137, v121, -v153
	v_fma_f32 v162, v138, v122, -v154
	v_fma_f32 v163, v139, v123, -v155
	v_cvt_pk_bf16_f32 v164, v156, v157
	v_cvt_pk_bf16_f32 v165, v158, v159
	v_cvt_pk_bf16_f32 v166, v160, v161
	v_cvt_pk_bf16_f32 v167, v162, v163
	global_store_dwordx4 v[172:173], v[164:167], off
	v_lshl_add_u64 v[172:173], v[172:173], 0, s[40:41]
	ds_read_b128 v[132:135], v112 offset:2560
	ds_read_b128 v[136:139], v112 offset:2576
	ds_read_b128 v[140:143], v113 offset:2560
	ds_read_b128 v[144:147], v113 offset:2576
	s_waitcnt lgkmcnt(0)
	v_mul_f32_e32 v148, v140, v124
	v_mul_f32_e32 v149, v141, v125
	v_mul_f32_e32 v150, v142, v126
	v_mul_f32_e32 v151, v143, v127
	v_mul_f32_e32 v152, v144, v128
	v_mul_f32_e32 v153, v145, v129
	v_mul_f32_e32 v154, v146, v130
	v_mul_f32_e32 v155, v147, v131
	v_fma_f32 v156, v132, v116, -v148
	v_fma_f32 v157, v133, v117, -v149
	v_fma_f32 v158, v134, v118, -v150
	v_fma_f32 v159, v135, v119, -v151
	v_fma_f32 v160, v136, v120, -v152
	v_fma_f32 v161, v137, v121, -v153
	v_fma_f32 v162, v138, v122, -v154
	v_fma_f32 v163, v139, v123, -v155
	v_cvt_pk_bf16_f32 v168, v156, v157
	v_cvt_pk_bf16_f32 v169, v158, v159
	v_cvt_pk_bf16_f32 v170, v160, v161
	v_cvt_pk_bf16_f32 v171, v162, v163
	global_store_dwordx4 v[172:173], v[168:171], off
	v_lshl_add_u64 v[172:173], v[172:173], 0, s[40:41]
	ds_read_b128 v[132:135], v112 offset:3072
	ds_read_b128 v[136:139], v112 offset:3088
	ds_read_b128 v[140:143], v113 offset:3072
	ds_read_b128 v[144:147], v113 offset:3088
	s_waitcnt lgkmcnt(0)
	v_mul_f32_e32 v148, v140, v124
	v_mul_f32_e32 v149, v141, v125
	v_mul_f32_e32 v150, v142, v126
	v_mul_f32_e32 v151, v143, v127
	v_mul_f32_e32 v152, v144, v128
	v_mul_f32_e32 v153, v145, v129
	v_mul_f32_e32 v154, v146, v130
	v_mul_f32_e32 v155, v147, v131
	v_fma_f32 v156, v132, v116, -v148
	v_fma_f32 v157, v133, v117, -v149
	v_fma_f32 v158, v134, v118, -v150
	v_fma_f32 v159, v135, v119, -v151
	v_fma_f32 v160, v136, v120, -v152
	v_fma_f32 v161, v137, v121, -v153
	v_fma_f32 v162, v138, v122, -v154
	v_fma_f32 v163, v139, v123, -v155
	v_cvt_pk_bf16_f32 v164, v156, v157
	v_cvt_pk_bf16_f32 v165, v158, v159
	v_cvt_pk_bf16_f32 v166, v160, v161
	v_cvt_pk_bf16_f32 v167, v162, v163
	global_store_dwordx4 v[172:173], v[164:167], off
	v_lshl_add_u64 v[172:173], v[172:173], 0, s[40:41]
	ds_read_b128 v[132:135], v112 offset:3584
	ds_read_b128 v[136:139], v112 offset:3600
	ds_read_b128 v[140:143], v113 offset:3584
	ds_read_b128 v[144:147], v113 offset:3600
	s_waitcnt lgkmcnt(0)
	v_mul_f32_e32 v148, v140, v124
	v_mul_f32_e32 v149, v141, v125
	v_mul_f32_e32 v150, v142, v126
	v_mul_f32_e32 v151, v143, v127
	v_mul_f32_e32 v152, v144, v128
	v_mul_f32_e32 v153, v145, v129
	v_mul_f32_e32 v154, v146, v130
	v_mul_f32_e32 v155, v147, v131
	v_fma_f32 v156, v132, v116, -v148
	v_fma_f32 v157, v133, v117, -v149
	v_fma_f32 v158, v134, v118, -v150
	v_fma_f32 v159, v135, v119, -v151
	v_fma_f32 v160, v136, v120, -v152
	v_fma_f32 v161, v137, v121, -v153
	v_fma_f32 v162, v138, v122, -v154
	v_fma_f32 v163, v139, v123, -v155
	v_cvt_pk_bf16_f32 v168, v156, v157
	v_cvt_pk_bf16_f32 v169, v158, v159
	v_cvt_pk_bf16_f32 v170, v160, v161
	v_cvt_pk_bf16_f32 v171, v162, v163
	global_store_dwordx4 v[172:173], v[168:171], off
	v_lshl_add_u64 v[172:173], v[172:173], 0, s[40:41]
	ds_read_b128 v[132:135], v112 offset:4096
	ds_read_b128 v[136:139], v112 offset:4112
	ds_read_b128 v[140:143], v113 offset:4096
	ds_read_b128 v[144:147], v113 offset:4112
	s_waitcnt lgkmcnt(0)
; DI u32x4 pack8(const float* f) { u32x4 w; w.x = pk2(f[0], f[1]); w.y = pk2(f[2], f[3]); w.z = pk2(f[4], f[5]); w.w = pk2(f[6], f[7]); return w; }
; DI void phase_s5pre(LAS unsigned char* lds, PP p, int l, int bid, int nblk) {
;     ...
;             } else { for (int i = 0; i < 8; ++i) { const int cc = (oc - 64) * 8 + i, ri = cc >> 6, pp = cc & 63;
;                 const float ar = apr[(t + 1) * 64 + pp], ai = api[(t + 1) * 64 + pp], cr = ccr[ho * 64 + pp], ci = cci[ho * 64 + pp];
;                 f[i] = ri == 0 ? (cr * ar - ci * ai) : -(cr * ai + ci * ar); } }
;             *(u32x4*)(bt2 + ((size_t)g * 512 + n) * 640 + oc * 8) = pack8(f); }
	v_mul_f32_e32 v148, v140, v124
	v_mul_f32_e32 v149, v141, v125
	v_mul_f32_e32 v150, v142, v126
	v_mul_f32_e32 v151, v143, v127
	v_mul_f32_e32 v152, v144, v128
	v_mul_f32_e32 v153, v145, v129
	v_mul_f32_e32 v154, v146, v130
	v_mul_f32_e32 v155, v147, v131
	v_fma_f32 v156, v132, v116, -v148
	v_fma_f32 v157, v133, v117, -v149
	v_fma_f32 v158, v134, v118, -v150
	v_fma_f32 v159, v135, v119, -v151
	v_fma_f32 v160, v136, v120, -v152
	v_fma_f32 v161, v137, v121, -v153
	v_fma_f32 v162, v138, v122, -v154
	v_fma_f32 v163, v139, v123, -v155
	v_cvt_pk_bf16_f32 v164, v156, v157
	v_cvt_pk_bf16_f32 v165, v158, v159
	v_cvt_pk_bf16_f32 v166, v160, v161
	v_cvt_pk_bf16_f32 v167, v162, v163
	global_store_dwordx4 v[172:173], v[164:167], off
	v_lshl_add_u64 v[172:173], v[172:173], 0, s[40:41]
	ds_read_b128 v[132:135], v112 offset:4608
	ds_read_b128 v[136:139], v112 offset:4624
	ds_read_b128 v[140:143], v113 offset:4608
	ds_read_b128 v[144:147], v113 offset:4624
	s_waitcnt lgkmcnt(0)
	v_mul_f32_e32 v148, v140, v124
	v_mul_f32_e32 v149, v141, v125
	v_mul_f32_e32 v150, v142, v126
	v_mul_f32_e32 v151, v143, v127
	v_mul_f32_e32 v152, v144, v128
	v_mul_f32_e32 v153, v145, v129
	v_mul_f32_e32 v154, v146, v130
	v_mul_f32_e32 v155, v147, v131
	v_fma_f32 v156, v132, v116, -v148
	v_fma_f32 v157, v133, v117, -v149
	v_fma_f32 v158, v134, v118, -v150
	v_fma_f32 v159, v135, v119, -v151
	v_fma_f32 v160, v136, v120, -v152
	v_fma_f32 v161, v137, v121, -v153
	v_fma_f32 v162, v138, v122, -v154
	v_fma_f32 v163, v139, v123, -v155
	v_cvt_pk_bf16_f32 v168, v156, v157
	v_cvt_pk_bf16_f32 v169, v158, v159
	v_cvt_pk_bf16_f32 v170, v160, v161
	v_cvt_pk_bf16_f32 v171, v162, v163
	global_store_dwordx4 v[172:173], v[168:171], off
	v_lshl_add_u64 v[172:173], v[172:173], 0, s[40:41]
	ds_read_b128 v[132:135], v112 offset:5120
	ds_read_b128 v[136:139], v112 offset:5136
	ds_read_b128 v[140:143], v113 offset:5120
	ds_read_b128 v[144:147], v113 offset:5136
	s_waitcnt lgkmcnt(0)
	v_mul_f32_e32 v148, v140, v124
	v_mul_f32_e32 v149, v141, v125
	v_mul_f32_e32 v150, v142, v126
	v_mul_f32_e32 v151, v143, v127
	v_mul_f32_e32 v152, v144, v128
	v_mul_f32_e32 v153, v145, v129
	v_mul_f32_e32 v154, v146, v130
	v_mul_f32_e32 v155, v147, v131
	v_fma_f32 v156, v132, v116, -v148
	v_fma_f32 v157, v133, v117, -v149
	v_fma_f32 v158, v134, v118, -v150
	v_fma_f32 v159, v135, v119, -v151
	v_fma_f32 v160, v136, v120, -v152
	v_fma_f32 v161, v137, v121, -v153
	v_fma_f32 v162, v138, v122, -v154
	v_fma_f32 v163, v139, v123, -v155
	v_cvt_pk_bf16_f32 v164, v156, v157
	v_cvt_pk_bf16_f32 v165, v158, v159
	v_cvt_pk_bf16_f32 v166, v160, v161
	v_cvt_pk_bf16_f32 v167, v162, v163
	global_store_dwordx4 v[172:173], v[164:167], off
	v_lshl_add_u64 v[172:173], v[172:173], 0, s[40:41]
	ds_read_b128 v[132:135], v112 offset:5632
	ds_read_b128 v[136:139], v112 offset:5648
	ds_read_b128 v[140:143], v113 offset:5632
	ds_read_b128 v[144:147], v113 offset:5648
	s_waitcnt lgkmcnt(0)
	v_mul_f32_e32 v148, v140, v124
	v_mul_f32_e32 v149, v141, v125
	v_mul_f32_e32 v150, v142, v126
	v_mul_f32_e32 v151, v143, v127
	v_mul_f32_e32 v152, v144, v128
	v_mul_f32_e32 v153, v145, v129
	v_mul_f32_e32 v154, v146, v130
	v_mul_f32_e32 v155, v147, v131
	v_fma_f32 v156, v132, v116, -v148
	v_fma_f32 v157, v133, v117, -v149
	v_fma_f32 v158, v134, v118, -v150
	v_fma_f32 v159, v135, v119, -v151
	v_fma_f32 v160, v136, v120, -v152
	v_fma_f32 v161, v137, v121, -v153
	v_fma_f32 v162, v138, v122, -v154
	v_fma_f32 v163, v139, v123, -v155
	v_cvt_pk_bf16_f32 v168, v156, v157
	v_cvt_pk_bf16_f32 v169, v158, v159
	v_cvt_pk_bf16_f32 v170, v160, v161
	v_cvt_pk_bf16_f32 v171, v162, v163
	global_store_dwordx4 v[172:173], v[168:171], off
	v_lshl_add_u64 v[172:173], v[172:173], 0, s[40:41]
	ds_read_b128 v[132:135], v112 offset:6144
	ds_read_b128 v[136:139], v112 offset:6160
	ds_read_b128 v[140:143], v113 offset:6144
	ds_read_b128 v[144:147], v113 offset:6160
	s_waitcnt lgkmcnt(0)
; DI u32x4 pack8(const float* f) { u32x4 w; w.x = pk2(f[0], f[1]); w.y = pk2(f[2], f[3]); w.z = pk2(f[4], f[5]); w.w = pk2(f[6], f[7]); return w; }
; DI void phase_s5pre(LAS unsigned char* lds, PP p, int l, int bid, int nblk) {
;     ...
;             } else { for (int i = 0; i < 8; ++i) { const int cc = (oc - 64) * 8 + i, ri = cc >> 6, pp = cc & 63;
;                 const float ar = apr[(t + 1) * 64 + pp], ai = api[(t + 1) * 64 + pp], cr = ccr[ho * 64 + pp], ci = cci[ho * 64 + pp];
;                 f[i] = ri == 0 ? (cr * ar - ci * ai) : -(cr * ai + ci * ar); } }
;             *(u32x4*)(bt2 + ((size_t)g * 512 + n) * 640 + oc * 8) = pack8(f); }
	v_mul_f32_e32 v148, v140, v124
	v_mul_f32_e32 v149, v141, v125
	v_mul_f32_e32 v150, v142, v126
	v_mul_f32_e32 v151, v143, v127
	v_mul_f32_e32 v152, v144, v128
	v_mul_f32_e32 v153, v145, v129
	v_mul_f32_e32 v154, v146, v130
	v_mul_f32_e32 v155, v147, v131
	v_fma_f32 v156, v132, v116, -v148
	v_fma_f32 v157, v133, v117, -v149
	v_fma_f32 v158, v134, v118, -v150
	v_fma_f32 v159, v135, v119, -v151
	v_fma_f32 v160, v136, v120, -v152
	v_fma_f32 v161, v137, v121, -v153
	v_fma_f32 v162, v138, v122, -v154
	v_fma_f32 v163, v139, v123, -v155
	v_cvt_pk_bf16_f32 v164, v156, v157
	v_cvt_pk_bf16_f32 v165, v158, v159
	v_cvt_pk_bf16_f32 v166, v160, v161
	v_cvt_pk_bf16_f32 v167, v162, v163
	global_store_dwordx4 v[172:173], v[164:167], off
	v_lshl_add_u64 v[172:173], v[172:173], 0, s[40:41]
	ds_read_b128 v[132:135], v112 offset:6656
	ds_read_b128 v[136:139], v112 offset:6672
	ds_read_b128 v[140:143], v113 offset:6656
	ds_read_b128 v[144:147], v113 offset:6672
	s_waitcnt lgkmcnt(0)
	v_mul_f32_e32 v148, v140, v124
	v_mul_f32_e32 v149, v141, v125
	v_mul_f32_e32 v150, v142, v126
	v_mul_f32_e32 v151, v143, v127
	v_mul_f32_e32 v152, v144, v128
	v_mul_f32_e32 v153, v145, v129
	v_mul_f32_e32 v154, v146, v130
	v_mul_f32_e32 v155, v147, v131
	v_fma_f32 v156, v132, v116, -v148
	v_fma_f32 v157, v133, v117, -v149
	v_fma_f32 v158, v134, v118, -v150
	v_fma_f32 v159, v135, v119, -v151
	v_fma_f32 v160, v136, v120, -v152
	v_fma_f32 v161, v137, v121, -v153
	v_fma_f32 v162, v138, v122, -v154
	v_fma_f32 v163, v139, v123, -v155
	v_cvt_pk_bf16_f32 v168, v156, v157
	v_cvt_pk_bf16_f32 v169, v158, v159
	v_cvt_pk_bf16_f32 v170, v160, v161
	v_cvt_pk_bf16_f32 v171, v162, v163
	global_store_dwordx4 v[172:173], v[168:171], off
	v_lshl_add_u64 v[172:173], v[172:173], 0, s[40:41]
	ds_read_b128 v[132:135], v112 offset:7168
	ds_read_b128 v[136:139], v112 offset:7184
	ds_read_b128 v[140:143], v113 offset:7168
	ds_read_b128 v[144:147], v113 offset:7184
	s_waitcnt lgkmcnt(0)
	v_mul_f32_e32 v148, v140, v124
	v_mul_f32_e32 v149, v141, v125
	v_mul_f32_e32 v150, v142, v126
	v_mul_f32_e32 v151, v143, v127
	v_mul_f32_e32 v152, v144, v128
	v_mul_f32_e32 v153, v145, v129
	v_mul_f32_e32 v154, v146, v130
	v_mul_f32_e32 v155, v147, v131
	v_fma_f32 v156, v132, v116, -v148
	v_fma_f32 v157, v133, v117, -v149
	v_fma_f32 v158, v134, v118, -v150
	v_fma_f32 v159, v135, v119, -v151
	v_fma_f32 v160, v136, v120, -v152
	v_fma_f32 v161, v137, v121, -v153
	v_fma_f32 v162, v138, v122, -v154
	v_fma_f32 v163, v139, v123, -v155
	v_cvt_pk_bf16_f32 v164, v156, v157
	v_cvt_pk_bf16_f32 v165, v158, v159
	v_cvt_pk_bf16_f32 v166, v160, v161
	v_cvt_pk_bf16_f32 v167, v162, v163
	global_store_dwordx4 v[172:173], v[164:167], off
	v_lshl_add_u64 v[172:173], v[172:173], 0, s[40:41]
	ds_read_b128 v[132:135], v112 offset:7680
	ds_read_b128 v[136:139], v112 offset:7696
	ds_read_b128 v[140:143], v113 offset:7680
	ds_read_b128 v[144:147], v113 offset:7696
	s_waitcnt lgkmcnt(0)
	v_mul_f32_e32 v148, v140, v124
	v_mul_f32_e32 v149, v141, v125
	v_mul_f32_e32 v150, v142, v126
	v_mul_f32_e32 v151, v143, v127
	v_mul_f32_e32 v152, v144, v128
	v_mul_f32_e32 v153, v145, v129
	v_mul_f32_e32 v154, v146, v130
	v_mul_f32_e32 v155, v147, v131
	v_fma_f32 v156, v132, v116, -v148
	v_fma_f32 v157, v133, v117, -v149
	v_fma_f32 v158, v134, v118, -v150
	v_fma_f32 v159, v135, v119, -v151
	v_fma_f32 v160, v136, v120, -v152
	v_fma_f32 v161, v137, v121, -v153
	v_fma_f32 v162, v138, v122, -v154
	v_fma_f32 v163, v139, v123, -v155
	v_cvt_pk_bf16_f32 v168, v156, v157
	v_cvt_pk_bf16_f32 v169, v158, v159
	v_cvt_pk_bf16_f32 v170, v160, v161
	v_cvt_pk_bf16_f32 v171, v162, v163
	global_store_dwordx4 v[172:173], v[168:171], off
	v_lshl_add_u64 v[172:173], v[172:173], 0, s[40:41]

; DI u32x4 pack8(const float* f) { u32x4 w; w.x = pk2(f[0], f[1]); w.y = pk2(f[2], f[3]); w.z = pk2(f[4], f[5]); w.w = pk2(f[6], f[7]); return w; }
; DI void phase_s5pre(LAS unsigned char* lds, PP p, int l, int bid, int nblk) {
;     ...
;         for (int id = tid; id < 512 * 80; id += NTHR) { const int n = id / 80, oc = id % 80, t = n >> 4, ho = n & 15; float f[8];
;             if (oc < 64) { const int s = oc >> 1, hi0 = (oc & 1) * 8;
;                 for (int i = 0; i < 8; ++i) f[i] = (s <= t) ? kt[(t - s) * 256 + ho * 16 + hi0 + i] : 0.f;
;             } else { for (int i = 0; i < 8; ++i) { const int cc = (oc - 64) * 8 + i, ri = cc >> 6, pp = cc & 63;
;                 const float ar = apr[(t + 1) * 64 + pp], ai = api[(t + 1) * 64 + pp], cr = ccr[ho * 64 + pp], ci = cci[ho * 64 + pp];
;                 f[i] = ri == 0 ? (cr * ar - ci * ai) : -(cr * ai + ci * ar); } }
;             *(u32x4*)(bt2 + ((size_t)g * 512 + n) * 640 + oc * 8) = pack8(f); }
.LBB0_1295:
	s_or_b64 exec, exec, s[2:3]
	s_waitcnt lgkmcnt(0)
	s_barrier
	s_and_saveexec_b64 s[2:3], s[28:29]
	s_cbranch_execz .LBB0_1318
	s_mul_i32 s34, s4, 0xa0000
	s_add_u32 s34, s20, s34
	s_addc_u32 s35, s21, 0
	s_mov_b64 s[38:39], 0x2800
	s_mov_b64 s[40:41], 0xa000
	v_lshrrev_b32_e32 v60, 6, v201
	v_and_b32_e32 v61, 63, v201
	v_lshrrev_b32_e32 v62, 1, v61
	v_and_b32_e32 v63, 1, v61
	v_lshlrev_b32_e32 v63, 5, v63
	v_lshl_add_u32 v64, v60, 6, v63
	v_add_u32_e32 v64, 0x8200, v64
	v_mul_u32_u24_e32 v68, 0x500, v60
	v_lshl_add_u32 v68, v61, 4, v68
	v_mov_b32_e32 v69, 0
	v_lshl_add_u64 v[68:69], s[34:35], 0, v[68:69]
	v_and_b32_e32 v148, 3, v60
	v_lshlrev_b32_e32 v148, 2, v148
	v_lshrrev_b32_e32 v149, 4, v61
	v_add_u32_e32 v148, v148, v149
	v_and_b32_e32 v149, 7, v61
	v_lshlrev_b32_e32 v149, 5, v149
	v_bfe_u32 v150, v61, 3, 1
	v_lshrrev_b32_e32 v151, 2, v60
	v_lshl_add_u32 v114, v148, 8, v149
	ds_read_b128 v[116:119], v114 offset:25088
	ds_read_b128 v[120:123], v114 offset:25104
	ds_read_b128 v[124:127], v114 offset:29184
	ds_read_b128 v[128:131], v114 offset:29200
	v_lshl_add_u32 v112, v151, 8, v149
	v_add_u32_e32 v112, 0x100, v112
	v_mul_u32_u24_e32 v152, 0x2100, v150
	v_add_u32_e32 v113, 0x2100, v112
	v_sub_u32_e32 v113, v113, v152
	v_add_u32_e32 v112, v112, v152
	v_lshlrev_b32_e32 v115, 31, v150
	v_lshrrev_b32_e32 v153, 4, v201
	v_mul_u32_u24_e32 v172, 0x500, v153
	v_and_b32_e32 v153, 15, v61
	v_lshl_add_u32 v172, v153, 4, v172
	v_add_u32_e32 v172, 0x400, v172
	v_mov_b32_e32 v173, 0
	v_lshl_add_u64 v[172:173], s[34:35], 0, v[172:173]
	s_waitcnt lgkmcnt(0)
	v_xor_b32_e32 v116, v115, v116
	v_xor_b32_e32 v117, v115, v117
	v_xor_b32_e32 v118, v115, v118
	v_xor_b32_e32 v119, v115, v119
	v_xor_b32_e32 v120, v115, v120
	v_xor_b32_e32 v121, v115, v121
	v_xor_b32_e32 v122, v115, v122
	v_xor_b32_e32 v123, v115, v123
	v_sub_u32_e32 v65, 0, v62
	v_max_i32_e32 v65, 0, v65
	v_lshl_add_u32 v66, v65, 10, v64
	ds_read_b128 v[72:75], v66
	ds_read_b128 v[76:79], v66 offset:16
	ds_read_b128 v[80:83], v66 offset:512
	ds_read_b128 v[84:87], v66 offset:528
	v_sub_u32_e32 v65, 1, v62
	v_max_i32_e32 v65, 0, v65
	v_lshl_add_u32 v66, v65, 10, v64
	ds_read_b128 v[88:91], v66
	ds_read_b128 v[92:95], v66 offset:16
	ds_read_b128 v[96:99], v66 offset:512
	ds_read_b128 v[100:103], v66 offset:528
	s_waitcnt lgkmcnt(4)
	v_cmp_ge_u32_e64 s[36:37], 0, v62
	v_cvt_pk_bf16_f32 v104, v72, v73
	v_cvt_pk_bf16_f32 v105, v74, v75
	v_cvt_pk_bf16_f32 v106, v76, v77
	v_cvt_pk_bf16_f32 v107, v78, v79
	v_cndmask_b32_e64 v104, 0, v104, s[36:37]
	v_cndmask_b32_e64 v105, 0, v105, s[36:37]
	v_cndmask_b32_e64 v106, 0, v106, s[36:37]
	v_cndmask_b32_e64 v107, 0, v107, s[36:37]
	global_store_dwordx4 v[68:69], v[104:107], off
	v_lshl_add_u64 v[68:69], v[68:69], 0, s[38:39]
	v_cvt_pk_bf16_f32 v108, v80, v81
	v_cvt_pk_bf16_f32 v109, v82, v83
	v_cvt_pk_bf16_f32 v110, v84, v85
	v_cvt_pk_bf16_f32 v111, v86, v87
	v_cndmask_b32_e64 v108, 0, v108, s[36:37]
	v_cndmask_b32_e64 v109, 0, v109, s[36:37]
	v_cndmask_b32_e64 v110, 0, v110, s[36:37]
	v_cndmask_b32_e64 v111, 0, v111, s[36:37]
	global_store_dwordx4 v[68:69], v[108:111], off
	v_lshl_add_u64 v[68:69], v[68:69], 0, s[38:39]
	v_sub_u32_e32 v65, 2, v62
	v_max_i32_e32 v65, 0, v65
	v_lshl_add_u32 v66, v65, 10, v64
	ds_read_b128 v[72:75], v66
	ds_read_b128 v[76:79], v66 offset:16
	ds_read_b128 v[80:83], v66 offset:512
	ds_read_b128 v[84:87], v66 offset:528
	s_waitcnt lgkmcnt(4)
	v_cmp_ge_u32_e64 s[36:37], 1, v62
	v_cvt_pk_bf16_f32 v104, v88, v89
	v_cvt_pk_bf16_f32 v105, v90, v91
	v_cvt_pk_bf16_f32 v106, v92, v93
	v_cvt_pk_bf16_f32 v107, v94, v95
	v_cndmask_b32_e64 v104, 0, v104, s[36:37]
	v_cndmask_b32_e64 v105, 0, v105, s[36:37]
	v_cndmask_b32_e64 v106, 0, v106, s[36:37]
	v_cndmask_b32_e64 v107, 0, v107, s[36:37]
	global_store_dwordx4 v[68:69], v[104:107], off
	v_lshl_add_u64 v[68:69], v[68:69], 0, s[38:39]
	v_cvt_pk_bf16_f32 v108, v96, v97
	v_cvt_pk_bf16_f32 v109, v98, v99
	v_cvt_pk_bf16_f32 v110, v100, v101
	v_cvt_pk_bf16_f32 v111, v102, v103
	v_cndmask_b32_e64 v108, 0, v108, s[36:37]
	v_cndmask_b32_e64 v109, 0, v109, s[36:37]
	v_cndmask_b32_e64 v110, 0, v110, s[36:37]
	v_cndmask_b32_e64 v111, 0, v111, s[36:37]
	global_store_dwordx4 v[68:69], v[108:111], off
	v_lshl_add_u64 v[68:69], v[68:69], 0, s[38:39]
	v_sub_u32_e32 v65, 3, v62
	v_max_i32_e32 v65, 0, v65
	v_lshl_add_u32 v66, v65, 10, v64
	ds_read_b128 v[88:91], v66
	ds_read_b128 v[92:95], v66 offset:16
	ds_read_b128 v[96:99], v66 offset:512
	ds_read_b128 v[100:103], v66 offset:528
	s_waitcnt lgkmcnt(4)
	v_cmp_ge_u32_e64 s[36:37], 2, v62
	v_cvt_pk_bf16_f32 v104, v72, v73
	v_cvt_pk_bf16_f32 v105, v74, v75
	v_cvt_pk_bf16_f32 v106, v76, v77
	v_cvt_pk_bf16_f32 v107, v78, v79
	v_cndmask_b32_e64 v104, 0, v104, s[36:37]
	v_cndmask_b32_e64 v105, 0, v105, s[36:37]
	v_cndmask_b32_e64 v106, 0, v106, s[36:37]
	v_cndmask_b32_e64 v107, 0, v107, s[36:37]
	global_store_dwordx4 v[68:69], v[104:107], off
	v_lshl_add_u64 v[68:69], v[68:69], 0, s[38:39]
	v_cvt_pk_bf16_f32 v108, v80, v81
	v_cvt_pk_bf16_f32 v109, v82, v83
	v_cvt_pk_bf16_f32 v110, v84, v85
	v_cvt_pk_bf16_f32 v111, v86, v87
	v_cndmask_b32_e64 v108, 0, v108, s[36:37]
	v_cndmask_b32_e64 v109, 0, v109, s[36:37]
	v_cndmask_b32_e64 v110, 0, v110, s[36:37]
	v_cndmask_b32_e64 v111, 0, v111, s[36:37]
	global_store_dwordx4 v[68:69], v[108:111], off
	v_lshl_add_u64 v[68:69], v[68:69], 0, s[38:39]
	v_sub_u32_e32 v65, 4, v62
	v_max_i32_e32 v65, 0, v65
	v_lshl_add_u32 v66, v65, 10, v64
	ds_read_b128 v[72:75], v66
	ds_read_b128 v[76:79], v66 offset:16
	ds_read_b128 v[80:83], v66 offset:512
	ds_read_b128 v[84:87], v66 offset:528
	s_waitcnt lgkmcnt(4)
; DI u32x4 pack8(const float* f) { u32x4 w; w.x = pk2(f[0], f[1]); w.y = pk2(f[2], f[3]); w.z = pk2(f[4], f[5]); w.w = pk2(f[6], f[7]); return w; }
; DI void phase_s5pre(LAS unsigned char* lds, PP p, int l, int bid, int nblk) {
;     ...
;         for (int id = tid; id < 512 * 80; id += NTHR) { const int n = id / 80, oc = id % 80, t = n >> 4, ho = n & 15; float f[8];
;             if (oc < 64) { const int s = oc >> 1, hi0 = (oc & 1) * 8;
;                 for (int i = 0; i < 8; ++i) f[i] = (s <= t) ? kt[(t - s) * 256 + ho * 16 + hi0 + i] : 0.f;
;             } else { for (int i = 0; i < 8; ++i) { const int cc = (oc - 64) * 8 + i, ri = cc >> 6, pp = cc & 63;
;                 const float ar = apr[(t + 1) * 64 + pp], ai = api[(t + 1) * 64 + pp], cr = ccr[ho * 64 + pp], ci = cci[ho * 64 + pp];
;                 f[i] = ri == 0 ? (cr * ar - ci * ai) : -(cr * ai + ci * ar); } }
;             *(u32x4*)(bt2 + ((size_t)g * 512 + n) * 640 + oc * 8) = pack8(f); }
	v_cmp_ge_u32_e64 s[36:37], 3, v62
	v_cvt_pk_bf16_f32 v104, v88, v89
	v_cvt_pk_bf16_f32 v105, v90, v91
	v_cvt_pk_bf16_f32 v106, v92, v93
	v_cvt_pk_bf16_f32 v107, v94, v95
	v_cndmask_b32_e64 v104, 0, v104, s[36:37]
	v_cndmask_b32_e64 v105, 0, v105, s[36:37]
	v_cndmask_b32_e64 v106, 0, v106, s[36:37]
	v_cndmask_b32_e64 v107, 0, v107, s[36:37]
	global_store_dwordx4 v[68:69], v[104:107], off
	v_lshl_add_u64 v[68:69], v[68:69], 0, s[38:39]
	v_cvt_pk_bf16_f32 v108, v96, v97
	v_cvt_pk_bf16_f32 v109, v98, v99
	v_cvt_pk_bf16_f32 v110, v100, v101
	v_cvt_pk_bf16_f32 v111, v102, v103
	v_cndmask_b32_e64 v108, 0, v108, s[36:37]
	v_cndmask_b32_e64 v109, 0, v109, s[36:37]
	v_cndmask_b32_e64 v110, 0, v110, s[36:37]
	v_cndmask_b32_e64 v111, 0, v111, s[36:37]
	global_store_dwordx4 v[68:69], v[108:111], off
	v_lshl_add_u64 v[68:69], v[68:69], 0, s[38:39]
	v_sub_u32_e32 v65, 5, v62
	v_max_i32_e32 v65, 0, v65
	v_lshl_add_u32 v66, v65, 10, v64
	ds_read_b128 v[88:91], v66
	ds_read_b128 v[92:95], v66 offset:16
	ds_read_b128 v[96:99], v66 offset:512
	ds_read_b128 v[100:103], v66 offset:528
	s_waitcnt lgkmcnt(4)
	v_cmp_ge_u32_e64 s[36:37], 4, v62
	v_cvt_pk_bf16_f32 v104, v72, v73
	v_cvt_pk_bf16_f32 v105, v74, v75
	v_cvt_pk_bf16_f32 v106, v76, v77
	v_cvt_pk_bf16_f32 v107, v78, v79
	v_cndmask_b32_e64 v104, 0, v104, s[36:37]
	v_cndmask_b32_e64 v105, 0, v105, s[36:37]
	v_cndmask_b32_e64 v106, 0, v106, s[36:37]
	v_cndmask_b32_e64 v107, 0, v107, s[36:37]
	global_store_dwordx4 v[68:69], v[104:107], off
	v_lshl_add_u64 v[68:69], v[68:69], 0, s[38:39]
	v_cvt_pk_bf16_f32 v108, v80, v81
	v_cvt_pk_bf16_f32 v109, v82, v83
	v_cvt_pk_bf16_f32 v110, v84, v85
	v_cvt_pk_bf16_f32 v111, v86, v87
	v_cndmask_b32_e64 v108, 0, v108, s[36:37]
	v_cndmask_b32_e64 v109, 0, v109, s[36:37]
	v_cndmask_b32_e64 v110, 0, v110, s[36:37]
	v_cndmask_b32_e64 v111, 0, v111, s[36:37]
	global_store_dwordx4 v[68:69], v[108:111], off
	v_lshl_add_u64 v[68:69], v[68:69], 0, s[38:39]
	v_sub_u32_e32 v65, 6, v62
	v_max_i32_e32 v65, 0, v65
	v_lshl_add_u32 v66, v65, 10, v64
	ds_read_b128 v[72:75], v66
	ds_read_b128 v[76:79], v66 offset:16
	ds_read_b128 v[80:83], v66 offset:512
	ds_read_b128 v[84:87], v66 offset:528
	s_waitcnt lgkmcnt(4)
	v_cmp_ge_u32_e64 s[36:37], 5, v62
	v_cvt_pk_bf16_f32 v104, v88, v89
	v_cvt_pk_bf16_f32 v105, v90, v91
	v_cvt_pk_bf16_f32 v106, v92, v93
	v_cvt_pk_bf16_f32 v107, v94, v95
	v_cndmask_b32_e64 v104, 0, v104, s[36:37]
	v_cndmask_b32_e64 v105, 0, v105, s[36:37]
	v_cndmask_b32_e64 v106, 0, v106, s[36:37]
	v_cndmask_b32_e64 v107, 0, v107, s[36:37]
	global_store_dwordx4 v[68:69], v[104:107], off
	v_lshl_add_u64 v[68:69], v[68:69], 0, s[38:39]
	v_cvt_pk_bf16_f32 v108, v96, v97
	v_cvt_pk_bf16_f32 v109, v98, v99
	v_cvt_pk_bf16_f32 v110, v100, v101
	v_cvt_pk_bf16_f32 v111, v102, v103
	v_cndmask_b32_e64 v108, 0, v108, s[36:37]
	v_cndmask_b32_e64 v109, 0, v109, s[36:37]
	v_cndmask_b32_e64 v110, 0, v110, s[36:37]
	v_cndmask_b32_e64 v111, 0, v111, s[36:37]
	global_store_dwordx4 v[68:69], v[108:111], off
	v_lshl_add_u64 v[68:69], v[68:69], 0, s[38:39]
	v_sub_u32_e32 v65, 7, v62
	v_max_i32_e32 v65, 0, v65
	v_lshl_add_u32 v66, v65, 10, v64
	ds_read_b128 v[88:91], v66
	ds_read_b128 v[92:95], v66 offset:16
	ds_read_b128 v[96:99], v66 offset:512
	ds_read_b128 v[100:103], v66 offset:528
	s_waitcnt lgkmcnt(4)
	v_cmp_ge_u32_e64 s[36:37], 6, v62
	v_cvt_pk_bf16_f32 v104, v72, v73
	v_cvt_pk_bf16_f32 v105, v74, v75
	v_cvt_pk_bf16_f32 v106, v76, v77
	v_cvt_pk_bf16_f32 v107, v78, v79
	v_cndmask_b32_e64 v104, 0, v104, s[36:37]
	v_cndmask_b32_e64 v105, 0, v105, s[36:37]
	v_cndmask_b32_e64 v106, 0, v106, s[36:37]
	v_cndmask_b32_e64 v107, 0, v107, s[36:37]
	global_store_dwordx4 v[68:69], v[104:107], off
	v_lshl_add_u64 v[68:69], v[68:69], 0, s[38:39]
	v_cvt_pk_bf16_f32 v108, v80, v81
	v_cvt_pk_bf16_f32 v109, v82, v83
	v_cvt_pk_bf16_f32 v110, v84, v85
	v_cvt_pk_bf16_f32 v111, v86, v87
	v_cndmask_b32_e64 v108, 0, v108, s[36:37]
	v_cndmask_b32_e64 v109, 0, v109, s[36:37]
	v_cndmask_b32_e64 v110, 0, v110, s[36:37]
	v_cndmask_b32_e64 v111, 0, v111, s[36:37]
	global_store_dwordx4 v[68:69], v[108:111], off
	v_lshl_add_u64 v[68:69], v[68:69], 0, s[38:39]
	v_sub_u32_e32 v65, 8, v62
	v_max_i32_e32 v65, 0, v65
	v_lshl_add_u32 v66, v65, 10, v64
	ds_read_b128 v[72:75], v66
	ds_read_b128 v[76:79], v66 offset:16
	ds_read_b128 v[80:83], v66 offset:512
	ds_read_b128 v[84:87], v66 offset:528
	s_waitcnt lgkmcnt(4)
	v_cmp_ge_u32_e64 s[36:37], 7, v62
	v_cvt_pk_bf16_f32 v104, v88, v89
	v_cvt_pk_bf16_f32 v105, v90, v91
	v_cvt_pk_bf16_f32 v106, v92, v93
	v_cvt_pk_bf16_f32 v107, v94, v95
	v_cndmask_b32_e64 v104, 0, v104, s[36:37]
	v_cndmask_b32_e64 v105, 0, v105, s[36:37]
	v_cndmask_b32_e64 v106, 0, v106, s[36:37]
	v_cndmask_b32_e64 v107, 0, v107, s[36:37]
	global_store_dwordx4 v[68:69], v[104:107], off
	v_lshl_add_u64 v[68:69], v[68:69], 0, s[38:39]
	v_cvt_pk_bf16_f32 v108, v96, v97
	v_cvt_pk_bf16_f32 v109, v98, v99
	v_cvt_pk_bf16_f32 v110, v100, v101
	v_cvt_pk_bf16_f32 v111, v102, v103
	v_cndmask_b32_e64 v108, 0, v108, s[36:37]
	v_cndmask_b32_e64 v109, 0, v109, s[36:37]
	v_cndmask_b32_e64 v110, 0, v110, s[36:37]
	v_cndmask_b32_e64 v111, 0, v111, s[36:37]
	global_store_dwordx4 v[68:69], v[108:111], off
	v_lshl_add_u64 v[68:69], v[68:69], 0, s[38:39]
	v_sub_u32_e32 v65, 9, v62
	v_max_i32_e32 v65, 0, v65
	v_lshl_add_u32 v66, v65, 10, v64
	ds_read_b128 v[88:91], v66
	ds_read_b128 v[92:95], v66 offset:16
	ds_read_b128 v[96:99], v66 offset:512
	ds_read_b128 v[100:103], v66 offset:528
	s_waitcnt lgkmcnt(4)
; DI u32x4 pack8(const float* f) { u32x4 w; w.x = pk2(f[0], f[1]); w.y = pk2(f[2], f[3]); w.z = pk2(f[4], f[5]); w.w = pk2(f[6], f[7]); return w; }
; DI void phase_s5pre(LAS unsigned char* lds, PP p, int l, int bid, int nblk) {
;     ...
;         for (int id = tid; id < 512 * 80; id += NTHR) { const int n = id / 80, oc = id % 80, t = n >> 4, ho = n & 15; float f[8];
;             if (oc < 64) { const int s = oc >> 1, hi0 = (oc & 1) * 8;
;                 for (int i = 0; i < 8; ++i) f[i] = (s <= t) ? kt[(t - s) * 256 + ho * 16 + hi0 + i] : 0.f;
;             } else { for (int i = 0; i < 8; ++i) { const int cc = (oc - 64) * 8 + i, ri = cc >> 6, pp = cc & 63;
;                 const float ar = apr[(t + 1) * 64 + pp], ai = api[(t + 1) * 64 + pp], cr = ccr[ho * 64 + pp], ci = cci[ho * 64 + pp];
;                 f[i] = ri == 0 ? (cr * ar - ci * ai) : -(cr * ai + ci * ar); } }
;             *(u32x4*)(bt2 + ((size_t)g * 512 + n) * 640 + oc * 8) = pack8(f); }
	v_cmp_ge_u32_e64 s[36:37], 8, v62
	v_cvt_pk_bf16_f32 v104, v72, v73
	v_cvt_pk_bf16_f32 v105, v74, v75
	v_cvt_pk_bf16_f32 v106, v76, v77
	v_cvt_pk_bf16_f32 v107, v78, v79
	v_cndmask_b32_e64 v104, 0, v104, s[36:37]
	v_cndmask_b32_e64 v105, 0, v105, s[36:37]
	v_cndmask_b32_e64 v106, 0, v106, s[36:37]
	v_cndmask_b32_e64 v107, 0, v107, s[36:37]
	global_store_dwordx4 v[68:69], v[104:107], off
	v_lshl_add_u64 v[68:69], v[68:69], 0, s[38:39]
	v_cvt_pk_bf16_f32 v108, v80, v81
	v_cvt_pk_bf16_f32 v109, v82, v83
	v_cvt_pk_bf16_f32 v110, v84, v85
	v_cvt_pk_bf16_f32 v111, v86, v87
	v_cndmask_b32_e64 v108, 0, v108, s[36:37]
	v_cndmask_b32_e64 v109, 0, v109, s[36:37]
	v_cndmask_b32_e64 v110, 0, v110, s[36:37]
	v_cndmask_b32_e64 v111, 0, v111, s[36:37]
	global_store_dwordx4 v[68:69], v[108:111], off
	v_lshl_add_u64 v[68:69], v[68:69], 0, s[38:39]
	v_sub_u32_e32 v65, 10, v62
	v_max_i32_e32 v65, 0, v65
	v_lshl_add_u32 v66, v65, 10, v64
	ds_read_b128 v[72:75], v66
	ds_read_b128 v[76:79], v66 offset:16
	ds_read_b128 v[80:83], v66 offset:512
	ds_read_b128 v[84:87], v66 offset:528
	s_waitcnt lgkmcnt(4)
	v_cmp_ge_u32_e64 s[36:37], 9, v62
	v_cvt_pk_bf16_f32 v104, v88, v89
	v_cvt_pk_bf16_f32 v105, v90, v91
	v_cvt_pk_bf16_f32 v106, v92, v93
	v_cvt_pk_bf16_f32 v107, v94, v95
	v_cndmask_b32_e64 v104, 0, v104, s[36:37]
	v_cndmask_b32_e64 v105, 0, v105, s[36:37]
	v_cndmask_b32_e64 v106, 0, v106, s[36:37]
	v_cndmask_b32_e64 v107, 0, v107, s[36:37]
	global_store_dwordx4 v[68:69], v[104:107], off
	v_lshl_add_u64 v[68:69], v[68:69], 0, s[38:39]
	v_cvt_pk_bf16_f32 v108, v96, v97
	v_cvt_pk_bf16_f32 v109, v98, v99
	v_cvt_pk_bf16_f32 v110, v100, v101
	v_cvt_pk_bf16_f32 v111, v102, v103
	v_cndmask_b32_e64 v108, 0, v108, s[36:37]
	v_cndmask_b32_e64 v109, 0, v109, s[36:37]
	v_cndmask_b32_e64 v110, 0, v110, s[36:37]
	v_cndmask_b32_e64 v111, 0, v111, s[36:37]
	global_store_dwordx4 v[68:69], v[108:111], off
	v_lshl_add_u64 v[68:69], v[68:69], 0, s[38:39]
	v_sub_u32_e32 v65, 11, v62
	v_max_i32_e32 v65, 0, v65
	v_lshl_add_u32 v66, v65, 10, v64
	ds_read_b128 v[88:91], v66
	ds_read_b128 v[92:95], v66 offset:16
	ds_read_b128 v[96:99], v66 offset:512
	ds_read_b128 v[100:103], v66 offset:528
	s_waitcnt lgkmcnt(4)
	v_cmp_ge_u32_e64 s[36:37], 10, v62
	v_cvt_pk_bf16_f32 v104, v72, v73
	v_cvt_pk_bf16_f32 v105, v74, v75
	v_cvt_pk_bf16_f32 v106, v76, v77
	v_cvt_pk_bf16_f32 v107, v78, v79
	v_cndmask_b32_e64 v104, 0, v104, s[36:37]
	v_cndmask_b32_e64 v105, 0, v105, s[36:37]
	v_cndmask_b32_e64 v106, 0, v106, s[36:37]
	v_cndmask_b32_e64 v107, 0, v107, s[36:37]
	global_store_dwordx4 v[68:69], v[104:107], off
	v_lshl_add_u64 v[68:69], v[68:69], 0, s[38:39]
	v_cvt_pk_bf16_f32 v108, v80, v81
	v_cvt_pk_bf16_f32 v109, v82, v83
	v_cvt_pk_bf16_f32 v110, v84, v85
	v_cvt_pk_bf16_f32 v111, v86, v87
	v_cndmask_b32_e64 v108, 0, v108, s[36:37]
	v_cndmask_b32_e64 v109, 0, v109, s[36:37]
	v_cndmask_b32_e64 v110, 0, v110, s[36:37]
	v_cndmask_b32_e64 v111, 0, v111, s[36:37]
	global_store_dwordx4 v[68:69], v[108:111], off
	v_lshl_add_u64 v[68:69], v[68:69], 0, s[38:39]
	v_sub_u32_e32 v65, 12, v62
	v_max_i32_e32 v65, 0, v65
	v_lshl_add_u32 v66, v65, 10, v64
	ds_read_b128 v[72:75], v66
	ds_read_b128 v[76:79], v66 offset:16
	ds_read_b128 v[80:83], v66 offset:512
	ds_read_b128 v[84:87], v66 offset:528
	s_waitcnt lgkmcnt(4)
	v_cmp_ge_u32_e64 s[36:37], 11, v62
	v_cvt_pk_bf16_f32 v104, v88, v89
	v_cvt_pk_bf16_f32 v105, v90, v91
	v_cvt_pk_bf16_f32 v106, v92, v93
	v_cvt_pk_bf16_f32 v107, v94, v95
	v_cndmask_b32_e64 v104, 0, v104, s[36:37]
	v_cndmask_b32_e64 v105, 0, v105, s[36:37]
	v_cndmask_b32_e64 v106, 0, v106, s[36:37]
	v_cndmask_b32_e64 v107, 0, v107, s[36:37]
	global_store_dwordx4 v[68:69], v[104:107], off
	v_lshl_add_u64 v[68:69], v[68:69], 0, s[38:39]
	v_cvt_pk_bf16_f32 v108, v96, v97
	v_cvt_pk_bf16_f32 v109, v98, v99
	v_cvt_pk_bf16_f32 v110, v100, v101
	v_cvt_pk_bf16_f32 v111, v102, v103
	v_cndmask_b32_e64 v108, 0, v108, s[36:37]
	v_cndmask_b32_e64 v109, 0, v109, s[36:37]
	v_cndmask_b32_e64 v110, 0, v110, s[36:37]
	v_cndmask_b32_e64 v111, 0, v111, s[36:37]
	global_store_dwordx4 v[68:69], v[108:111], off
	v_lshl_add_u64 v[68:69], v[68:69], 0, s[38:39]
	v_sub_u32_e32 v65, 13, v62
	v_max_i32_e32 v65, 0, v65
	v_lshl_add_u32 v66, v65, 10, v64
	ds_read_b128 v[88:91], v66
	ds_read_b128 v[92:95], v66 offset:16
	ds_read_b128 v[96:99], v66 offset:512
	ds_read_b128 v[100:103], v66 offset:528
	s_waitcnt lgkmcnt(4)
	v_cmp_ge_u32_e64 s[36:37], 12, v62
	v_cvt_pk_bf16_f32 v104, v72, v73
	v_cvt_pk_bf16_f32 v105, v74, v75
	v_cvt_pk_bf16_f32 v106, v76, v77
	v_cvt_pk_bf16_f32 v107, v78, v79
	v_cndmask_b32_e64 v104, 0, v104, s[36:37]
	v_cndmask_b32_e64 v105, 0, v105, s[36:37]
	v_cndmask_b32_e64 v106, 0, v106, s[36:37]
	v_cndmask_b32_e64 v107, 0, v107, s[36:37]
	global_store_dwordx4 v[68:69], v[104:107], off
	v_lshl_add_u64 v[68:69], v[68:69], 0, s[38:39]
	v_cvt_pk_bf16_f32 v108, v80, v81
	v_cvt_pk_bf16_f32 v109, v82, v83
	v_cvt_pk_bf16_f32 v110, v84, v85
	v_cvt_pk_bf16_f32 v111, v86, v87
	v_cndmask_b32_e64 v108, 0, v108, s[36:37]
	v_cndmask_b32_e64 v109, 0, v109, s[36:37]
	v_cndmask_b32_e64 v110, 0, v110, s[36:37]
	v_cndmask_b32_e64 v111, 0, v111, s[36:37]
	global_store_dwordx4 v[68:69], v[108:111], off
	v_lshl_add_u64 v[68:69], v[68:69], 0, s[38:39]
	v_sub_u32_e32 v65, 14, v62
	v_max_i32_e32 v65, 0, v65
	v_lshl_add_u32 v66, v65, 10, v64
	ds_read_b128 v[72:75], v66
	ds_read_b128 v[76:79], v66 offset:16
	ds_read_b128 v[80:83], v66 offset:512
	ds_read_b128 v[84:87], v66 offset:528
	s_waitcnt lgkmcnt(4)
; DI u32x4 pack8(const float* f) { u32x4 w; w.x = pk2(f[0], f[1]); w.y = pk2(f[2], f[3]); w.z = pk2(f[4], f[5]); w.w = pk2(f[6], f[7]); return w; }
; DI void phase_s5pre(LAS unsigned char* lds, PP p, int l, int bid, int nblk) {
;     ...
;         for (int id = tid; id < 512 * 80; id += NTHR) { const int n = id / 80, oc = id % 80, t = n >> 4, ho = n & 15; float f[8];
;             if (oc < 64) { const int s = oc >> 1, hi0 = (oc & 1) * 8;
;                 for (int i = 0; i < 8; ++i) f[i] = (s <= t) ? kt[(t - s) * 256 + ho * 16 + hi0 + i] : 0.f;
;             } else { for (int i = 0; i < 8; ++i) { const int cc = (oc - 64) * 8 + i, ri = cc >> 6, pp = cc & 63;
;                 const float ar = apr[(t + 1) * 64 + pp], ai = api[(t + 1) * 64 + pp], cr = ccr[ho * 64 + pp], ci = cci[ho * 64 + pp];
;                 f[i] = ri == 0 ? (cr * ar - ci * ai) : -(cr * ai + ci * ar); } }
;             *(u32x4*)(bt2 + ((size_t)g * 512 + n) * 640 + oc * 8) = pack8(f); }
	v_cmp_ge_u32_e64 s[36:37], 13, v62
	v_cvt_pk_bf16_f32 v104, v88, v89
	v_cvt_pk_bf16_f32 v105, v90, v91
	v_cvt_pk_bf16_f32 v106, v92, v93
	v_cvt_pk_bf16_f32 v107, v94, v95
	v_cndmask_b32_e64 v104, 0, v104, s[36:37]
	v_cndmask_b32_e64 v105, 0, v105, s[36:37]
	v_cndmask_b32_e64 v106, 0, v106, s[36:37]
	v_cndmask_b32_e64 v107, 0, v107, s[36:37]
	global_store_dwordx4 v[68:69], v[104:107], off
	v_lshl_add_u64 v[68:69], v[68:69], 0, s[38:39]
	v_cvt_pk_bf16_f32 v108, v96, v97
	v_cvt_pk_bf16_f32 v109, v98, v99
	v_cvt_pk_bf16_f32 v110, v100, v101
	v_cvt_pk_bf16_f32 v111, v102, v103
	v_cndmask_b32_e64 v108, 0, v108, s[36:37]
	v_cndmask_b32_e64 v109, 0, v109, s[36:37]
	v_cndmask_b32_e64 v110, 0, v110, s[36:37]
	v_cndmask_b32_e64 v111, 0, v111, s[36:37]
	global_store_dwordx4 v[68:69], v[108:111], off
	v_lshl_add_u64 v[68:69], v[68:69], 0, s[38:39]
	v_sub_u32_e32 v65, 15, v62
	v_max_i32_e32 v65, 0, v65
	v_lshl_add_u32 v66, v65, 10, v64
	ds_read_b128 v[88:91], v66
	ds_read_b128 v[92:95], v66 offset:16
	ds_read_b128 v[96:99], v66 offset:512
	ds_read_b128 v[100:103], v66 offset:528
	s_waitcnt lgkmcnt(4)
	v_cmp_ge_u32_e64 s[36:37], 14, v62
	v_cvt_pk_bf16_f32 v104, v72, v73
	v_cvt_pk_bf16_f32 v105, v74, v75
	v_cvt_pk_bf16_f32 v106, v76, v77
	v_cvt_pk_bf16_f32 v107, v78, v79
	v_cndmask_b32_e64 v104, 0, v104, s[36:37]
	v_cndmask_b32_e64 v105, 0, v105, s[36:37]
	v_cndmask_b32_e64 v106, 0, v106, s[36:37]
	v_cndmask_b32_e64 v107, 0, v107, s[36:37]
	global_store_dwordx4 v[68:69], v[104:107], off
	v_lshl_add_u64 v[68:69], v[68:69], 0, s[38:39]
	v_cvt_pk_bf16_f32 v108, v80, v81
	v_cvt_pk_bf16_f32 v109, v82, v83
	v_cvt_pk_bf16_f32 v110, v84, v85
	v_cvt_pk_bf16_f32 v111, v86, v87
	v_cndmask_b32_e64 v108, 0, v108, s[36:37]
	v_cndmask_b32_e64 v109, 0, v109, s[36:37]
	v_cndmask_b32_e64 v110, 0, v110, s[36:37]
	v_cndmask_b32_e64 v111, 0, v111, s[36:37]
	global_store_dwordx4 v[68:69], v[108:111], off
	v_lshl_add_u64 v[68:69], v[68:69], 0, s[38:39]
	v_sub_u32_e32 v65, 16, v62
	v_max_i32_e32 v65, 0, v65
	v_lshl_add_u32 v66, v65, 10, v64
	ds_read_b128 v[72:75], v66
	ds_read_b128 v[76:79], v66 offset:16
	ds_read_b128 v[80:83], v66 offset:512
	ds_read_b128 v[84:87], v66 offset:528
	s_waitcnt lgkmcnt(4)
	v_cmp_ge_u32_e64 s[36:37], 15, v62
	v_cvt_pk_bf16_f32 v104, v88, v89
	v_cvt_pk_bf16_f32 v105, v90, v91
	v_cvt_pk_bf16_f32 v106, v92, v93
	v_cvt_pk_bf16_f32 v107, v94, v95
	v_cndmask_b32_e64 v104, 0, v104, s[36:37]
	v_cndmask_b32_e64 v105, 0, v105, s[36:37]
	v_cndmask_b32_e64 v106, 0, v106, s[36:37]
	v_cndmask_b32_e64 v107, 0, v107, s[36:37]
	global_store_dwordx4 v[68:69], v[104:107], off
	v_lshl_add_u64 v[68:69], v[68:69], 0, s[38:39]
	v_cvt_pk_bf16_f32 v108, v96, v97
	v_cvt_pk_bf16_f32 v109, v98, v99
	v_cvt_pk_bf16_f32 v110, v100, v101
	v_cvt_pk_bf16_f32 v111, v102, v103
	v_cndmask_b32_e64 v108, 0, v108, s[36:37]
	v_cndmask_b32_e64 v109, 0, v109, s[36:37]
	v_cndmask_b32_e64 v110, 0, v110, s[36:37]
	v_cndmask_b32_e64 v111, 0, v111, s[36:37]
	global_store_dwordx4 v[68:69], v[108:111], off
	v_lshl_add_u64 v[68:69], v[68:69], 0, s[38:39]
	v_sub_u32_e32 v65, 17, v62
	v_max_i32_e32 v65, 0, v65
	v_lshl_add_u32 v66, v65, 10, v64
	ds_read_b128 v[88:91], v66
	ds_read_b128 v[92:95], v66 offset:16
	ds_read_b128 v[96:99], v66 offset:512
	ds_read_b128 v[100:103], v66 offset:528
	s_waitcnt lgkmcnt(4)
	v_cmp_ge_u32_e64 s[36:37], 16, v62
	v_cvt_pk_bf16_f32 v104, v72, v73
	v_cvt_pk_bf16_f32 v105, v74, v75
	v_cvt_pk_bf16_f32 v106, v76, v77
	v_cvt_pk_bf16_f32 v107, v78, v79
	v_cndmask_b32_e64 v104, 0, v104, s[36:37]
	v_cndmask_b32_e64 v105, 0, v105, s[36:37]
	v_cndmask_b32_e64 v106, 0, v106, s[36:37]
	v_cndmask_b32_e64 v107, 0, v107, s[36:37]
	global_store_dwordx4 v[68:69], v[104:107], off
	v_lshl_add_u64 v[68:69], v[68:69], 0, s[38:39]
	v_cvt_pk_bf16_f32 v108, v80, v81
	v_cvt_pk_bf16_f32 v109, v82, v83
	v_cvt_pk_bf16_f32 v110, v84, v85
	v_cvt_pk_bf16_f32 v111, v86, v87
	v_cndmask_b32_e64 v108, 0, v108, s[36:37]
	v_cndmask_b32_e64 v109, 0, v109, s[36:37]
	v_cndmask_b32_e64 v110, 0, v110, s[36:37]
	v_cndmask_b32_e64 v111, 0, v111, s[36:37]
	global_store_dwordx4 v[68:69], v[108:111], off
	v_lshl_add_u64 v[68:69], v[68:69], 0, s[38:39]
	v_sub_u32_e32 v65, 18, v62
	v_max_i32_e32 v65, 0, v65
	v_lshl_add_u32 v66, v65, 10, v64
	ds_read_b128 v[72:75], v66
	ds_read_b128 v[76:79], v66 offset:16
	ds_read_b128 v[80:83], v66 offset:512
	ds_read_b128 v[84:87], v66 offset:528
	s_waitcnt lgkmcnt(4)
	v_cmp_ge_u32_e64 s[36:37], 17, v62
	v_cvt_pk_bf16_f32 v104, v88, v89
	v_cvt_pk_bf16_f32 v105, v90, v91
	v_cvt_pk_bf16_f32 v106, v92, v93
	v_cvt_pk_bf16_f32 v107, v94, v95
	v_cndmask_b32_e64 v104, 0, v104, s[36:37]
	v_cndmask_b32_e64 v105, 0, v105, s[36:37]
	v_cndmask_b32_e64 v106, 0, v106, s[36:37]
	v_cndmask_b32_e64 v107, 0, v107, s[36:37]
	global_store_dwordx4 v[68:69], v[104:107], off
	v_lshl_add_u64 v[68:69], v[68:69], 0, s[38:39]
	v_cvt_pk_bf16_f32 v108, v96, v97
	v_cvt_pk_bf16_f32 v109, v98, v99
	v_cvt_pk_bf16_f32 v110, v100, v101
	v_cvt_pk_bf16_f32 v111, v102, v103
	v_cndmask_b32_e64 v108, 0, v108, s[36:37]
	v_cndmask_b32_e64 v109, 0, v109, s[36:37]
	v_cndmask_b32_e64 v110, 0, v110, s[36:37]
	v_cndmask_b32_e64 v111, 0, v111, s[36:37]
	global_store_dwordx4 v[68:69], v[108:111], off
	v_lshl_add_u64 v[68:69], v[68:69], 0, s[38:39]
	v_sub_u32_e32 v65, 19, v62
	v_max_i32_e32 v65, 0, v65
	v_lshl_add_u32 v66, v65, 10, v64
	ds_read_b128 v[88:91], v66
	ds_read_b128 v[92:95], v66 offset:16
	ds_read_b128 v[96:99], v66 offset:512
	ds_read_b128 v[100:103], v66 offset:528
	s_waitcnt lgkmcnt(4)
; DI u32x4 pack8(const float* f) { u32x4 w; w.x = pk2(f[0], f[1]); w.y = pk2(f[2], f[3]); w.z = pk2(f[4], f[5]); w.w = pk2(f[6], f[7]); return w; }
; DI void phase_s5pre(LAS unsigned char* lds, PP p, int l, int bid, int nblk) {
;     ...
;         for (int id = tid; id < 512 * 80; id += NTHR) { const int n = id / 80, oc = id % 80, t = n >> 4, ho = n & 15; float f[8];
;             if (oc < 64) { const int s = oc >> 1, hi0 = (oc & 1) * 8;
;                 for (int i = 0; i < 8; ++i) f[i] = (s <= t) ? kt[(t - s) * 256 + ho * 16 + hi0 + i] : 0.f;
;             } else { for (int i = 0; i < 8; ++i) { const int cc = (oc - 64) * 8 + i, ri = cc >> 6, pp = cc & 63;
;                 const float ar = apr[(t + 1) * 64 + pp], ai = api[(t + 1) * 64 + pp], cr = ccr[ho * 64 + pp], ci = cci[ho * 64 + pp];
;                 f[i] = ri == 0 ? (cr * ar - ci * ai) : -(cr * ai + ci * ar); } }
;             *(u32x4*)(bt2 + ((size_t)g * 512 + n) * 640 + oc * 8) = pack8(f); }
	v_cmp_ge_u32_e64 s[36:37], 18, v62
	v_cvt_pk_bf16_f32 v104, v72, v73
	v_cvt_pk_bf16_f32 v105, v74, v75
	v_cvt_pk_bf16_f32 v106, v76, v77
	v_cvt_pk_bf16_f32 v107, v78, v79
	v_cndmask_b32_e64 v104, 0, v104, s[36:37]
	v_cndmask_b32_e64 v105, 0, v105, s[36:37]
	v_cndmask_b32_e64 v106, 0, v106, s[36:37]
	v_cndmask_b32_e64 v107, 0, v107, s[36:37]
	global_store_dwordx4 v[68:69], v[104:107], off
	v_lshl_add_u64 v[68:69], v[68:69], 0, s[38:39]
	v_cvt_pk_bf16_f32 v108, v80, v81
	v_cvt_pk_bf16_f32 v109, v82, v83
	v_cvt_pk_bf16_f32 v110, v84, v85
	v_cvt_pk_bf16_f32 v111, v86, v87
	v_cndmask_b32_e64 v108, 0, v108, s[36:37]
	v_cndmask_b32_e64 v109, 0, v109, s[36:37]
	v_cndmask_b32_e64 v110, 0, v110, s[36:37]
	v_cndmask_b32_e64 v111, 0, v111, s[36:37]
	global_store_dwordx4 v[68:69], v[108:111], off
	v_lshl_add_u64 v[68:69], v[68:69], 0, s[38:39]
	v_sub_u32_e32 v65, 20, v62
	v_max_i32_e32 v65, 0, v65
	v_lshl_add_u32 v66, v65, 10, v64
	ds_read_b128 v[72:75], v66
	ds_read_b128 v[76:79], v66 offset:16
	ds_read_b128 v[80:83], v66 offset:512
	ds_read_b128 v[84:87], v66 offset:528
	s_waitcnt lgkmcnt(4)
	v_cmp_ge_u32_e64 s[36:37], 19, v62
	v_cvt_pk_bf16_f32 v104, v88, v89
	v_cvt_pk_bf16_f32 v105, v90, v91
	v_cvt_pk_bf16_f32 v106, v92, v93
	v_cvt_pk_bf16_f32 v107, v94, v95
	v_cndmask_b32_e64 v104, 0, v104, s[36:37]
	v_cndmask_b32_e64 v105, 0, v105, s[36:37]
	v_cndmask_b32_e64 v106, 0, v106, s[36:37]
	v_cndmask_b32_e64 v107, 0, v107, s[36:37]
	global_store_dwordx4 v[68:69], v[104:107], off
	v_lshl_add_u64 v[68:69], v[68:69], 0, s[38:39]
	v_cvt_pk_bf16_f32 v108, v96, v97
	v_cvt_pk_bf16_f32 v109, v98, v99
	v_cvt_pk_bf16_f32 v110, v100, v101
	v_cvt_pk_bf16_f32 v111, v102, v103
	v_cndmask_b32_e64 v108, 0, v108, s[36:37]
	v_cndmask_b32_e64 v109, 0, v109, s[36:37]
	v_cndmask_b32_e64 v110, 0, v110, s[36:37]
	v_cndmask_b32_e64 v111, 0, v111, s[36:37]
	global_store_dwordx4 v[68:69], v[108:111], off
	v_lshl_add_u64 v[68:69], v[68:69], 0, s[38:39]
	v_sub_u32_e32 v65, 21, v62
	v_max_i32_e32 v65, 0, v65
	v_lshl_add_u32 v66, v65, 10, v64
	ds_read_b128 v[88:91], v66
	ds_read_b128 v[92:95], v66 offset:16
	ds_read_b128 v[96:99], v66 offset:512
	ds_read_b128 v[100:103], v66 offset:528
	s_waitcnt lgkmcnt(4)
	v_cmp_ge_u32_e64 s[36:37], 20, v62
	v_cvt_pk_bf16_f32 v104, v72, v73
	v_cvt_pk_bf16_f32 v105, v74, v75
	v_cvt_pk_bf16_f32 v106, v76, v77
	v_cvt_pk_bf16_f32 v107, v78, v79
	v_cndmask_b32_e64 v104, 0, v104, s[36:37]
	v_cndmask_b32_e64 v105, 0, v105, s[36:37]
	v_cndmask_b32_e64 v106, 0, v106, s[36:37]
	v_cndmask_b32_e64 v107, 0, v107, s[36:37]
	global_store_dwordx4 v[68:69], v[104:107], off
	v_lshl_add_u64 v[68:69], v[68:69], 0, s[38:39]
	v_cvt_pk_bf16_f32 v108, v80, v81
	v_cvt_pk_bf16_f32 v109, v82, v83
	v_cvt_pk_bf16_f32 v110, v84, v85
	v_cvt_pk_bf16_f32 v111, v86, v87
	v_cndmask_b32_e64 v108, 0, v108, s[36:37]
	v_cndmask_b32_e64 v109, 0, v109, s[36:37]
	v_cndmask_b32_e64 v110, 0, v110, s[36:37]
	v_cndmask_b32_e64 v111, 0, v111, s[36:37]
	global_store_dwordx4 v[68:69], v[108:111], off
	v_lshl_add_u64 v[68:69], v[68:69], 0, s[38:39]
	v_sub_u32_e32 v65, 22, v62
	v_max_i32_e32 v65, 0, v65
	v_lshl_add_u32 v66, v65, 10, v64
	ds_read_b128 v[72:75], v66
	ds_read_b128 v[76:79], v66 offset:16
	ds_read_b128 v[80:83], v66 offset:512
	ds_read_b128 v[84:87], v66 offset:528
	s_waitcnt lgkmcnt(4)
	v_cmp_ge_u32_e64 s[36:37], 21, v62
	v_cvt_pk_bf16_f32 v104, v88, v89
	v_cvt_pk_bf16_f32 v105, v90, v91
	v_cvt_pk_bf16_f32 v106, v92, v93
	v_cvt_pk_bf16_f32 v107, v94, v95
	v_cndmask_b32_e64 v104, 0, v104, s[36:37]
	v_cndmask_b32_e64 v105, 0, v105, s[36:37]
	v_cndmask_b32_e64 v106, 0, v106, s[36:37]
	v_cndmask_b32_e64 v107, 0, v107, s[36:37]
	global_store_dwordx4 v[68:69], v[104:107], off
	v_lshl_add_u64 v[68:69], v[68:69], 0, s[38:39]
	v_cvt_pk_bf16_f32 v108, v96, v97
	v_cvt_pk_bf16_f32 v109, v98, v99
	v_cvt_pk_bf16_f32 v110, v100, v101
	v_cvt_pk_bf16_f32 v111, v102, v103
	v_cndmask_b32_e64 v108, 0, v108, s[36:37]
	v_cndmask_b32_e64 v109, 0, v109, s[36:37]
	v_cndmask_b32_e64 v110, 0, v110, s[36:37]
	v_cndmask_b32_e64 v111, 0, v111, s[36:37]
	global_store_dwordx4 v[68:69], v[108:111], off
	v_lshl_add_u64 v[68:69], v[68:69], 0, s[38:39]
	v_sub_u32_e32 v65, 23, v62
	v_max_i32_e32 v65, 0, v65
	v_lshl_add_u32 v66, v65, 10, v64
	ds_read_b128 v[88:91], v66
	ds_read_b128 v[92:95], v66 offset:16
	ds_read_b128 v[96:99], v66 offset:512
	ds_read_b128 v[100:103], v66 offset:528
	s_waitcnt lgkmcnt(4)
	v_cmp_ge_u32_e64 s[36:37], 22, v62
	v_cvt_pk_bf16_f32 v104, v72, v73
	v_cvt_pk_bf16_f32 v105, v74, v75
	v_cvt_pk_bf16_f32 v106, v76, v77
	v_cvt_pk_bf16_f32 v107, v78, v79
	v_cndmask_b32_e64 v104, 0, v104, s[36:37]
	v_cndmask_b32_e64 v105, 0, v105, s[36:37]
	v_cndmask_b32_e64 v106, 0, v106, s[36:37]
	v_cndmask_b32_e64 v107, 0, v107, s[36:37]
	global_store_dwordx4 v[68:69], v[104:107], off
	v_lshl_add_u64 v[68:69], v[68:69], 0, s[38:39]
	v_cvt_pk_bf16_f32 v108, v80, v81
	v_cvt_pk_bf16_f32 v109, v82, v83
	v_cvt_pk_bf16_f32 v110, v84, v85
	v_cvt_pk_bf16_f32 v111, v86, v87
	v_cndmask_b32_e64 v108, 0, v108, s[36:37]
	v_cndmask_b32_e64 v109, 0, v109, s[36:37]
	v_cndmask_b32_e64 v110, 0, v110, s[36:37]
	v_cndmask_b32_e64 v111, 0, v111, s[36:37]
	global_store_dwordx4 v[68:69], v[108:111], off
	v_lshl_add_u64 v[68:69], v[68:69], 0, s[38:39]
	v_sub_u32_e32 v65, 24, v62
	v_max_i32_e32 v65, 0, v65
	v_lshl_add_u32 v66, v65, 10, v64
	ds_read_b128 v[72:75], v66
	ds_read_b128 v[76:79], v66 offset:16
	ds_read_b128 v[80:83], v66 offset:512
	ds_read_b128 v[84:87], v66 offset:528
	s_waitcnt lgkmcnt(4)
; DI u32x4 pack8(const float* f) { u32x4 w; w.x = pk2(f[0], f[1]); w.y = pk2(f[2], f[3]); w.z = pk2(f[4], f[5]); w.w = pk2(f[6], f[7]); return w; }
; DI void phase_s5pre(LAS unsigned char* lds, PP p, int l, int bid, int nblk) {
;     ...
;         for (int id = tid; id < 512 * 80; id += NTHR) { const int n = id / 80, oc = id % 80, t = n >> 4, ho = n & 15; float f[8];
;             if (oc < 64) { const int s = oc >> 1, hi0 = (oc & 1) * 8;
;                 for (int i = 0; i < 8; ++i) f[i] = (s <= t) ? kt[(t - s) * 256 + ho * 16 + hi0 + i] : 0.f;
;             } else { for (int i = 0; i < 8; ++i) { const int cc = (oc - 64) * 8 + i, ri = cc >> 6, pp = cc & 63;
;                 const float ar = apr[(t + 1) * 64 + pp], ai = api[(t + 1) * 64 + pp], cr = ccr[ho * 64 + pp], ci = cci[ho * 64 + pp];
;                 f[i] = ri == 0 ? (cr * ar - ci * ai) : -(cr * ai + ci * ar); } }
;             *(u32x4*)(bt2 + ((size_t)g * 512 + n) * 640 + oc * 8) = pack8(f); }
	v_cmp_ge_u32_e64 s[36:37], 23, v62
	v_cvt_pk_bf16_f32 v104, v88, v89
	v_cvt_pk_bf16_f32 v105, v90, v91
	v_cvt_pk_bf16_f32 v106, v92, v93
	v_cvt_pk_bf16_f32 v107, v94, v95
	v_cndmask_b32_e64 v104, 0, v104, s[36:37]
	v_cndmask_b32_e64 v105, 0, v105, s[36:37]
	v_cndmask_b32_e64 v106, 0, v106, s[36:37]
	v_cndmask_b32_e64 v107, 0, v107, s[36:37]
	global_store_dwordx4 v[68:69], v[104:107], off
	v_lshl_add_u64 v[68:69], v[68:69], 0, s[38:39]
	v_cvt_pk_bf16_f32 v108, v96, v97
	v_cvt_pk_bf16_f32 v109, v98, v99
	v_cvt_pk_bf16_f32 v110, v100, v101
	v_cvt_pk_bf16_f32 v111, v102, v103
	v_cndmask_b32_e64 v108, 0, v108, s[36:37]
	v_cndmask_b32_e64 v109, 0, v109, s[36:37]
	v_cndmask_b32_e64 v110, 0, v110, s[36:37]
	v_cndmask_b32_e64 v111, 0, v111, s[36:37]
	global_store_dwordx4 v[68:69], v[108:111], off
	v_lshl_add_u64 v[68:69], v[68:69], 0, s[38:39]
	v_sub_u32_e32 v65, 25, v62
	v_max_i32_e32 v65, 0, v65
	v_lshl_add_u32 v66, v65, 10, v64
	ds_read_b128 v[88:91], v66
	ds_read_b128 v[92:95], v66 offset:16
	ds_read_b128 v[96:99], v66 offset:512
	ds_read_b128 v[100:103], v66 offset:528
	s_waitcnt lgkmcnt(4)
	v_cmp_ge_u32_e64 s[36:37], 24, v62
	v_cvt_pk_bf16_f32 v104, v72, v73
	v_cvt_pk_bf16_f32 v105, v74, v75
	v_cvt_pk_bf16_f32 v106, v76, v77
	v_cvt_pk_bf16_f32 v107, v78, v79
	v_cndmask_b32_e64 v104, 0, v104, s[36:37]
	v_cndmask_b32_e64 v105, 0, v105, s[36:37]
	v_cndmask_b32_e64 v106, 0, v106, s[36:37]
	v_cndmask_b32_e64 v107, 0, v107, s[36:37]
	global_store_dwordx4 v[68:69], v[104:107], off
	v_lshl_add_u64 v[68:69], v[68:69], 0, s[38:39]
	v_cvt_pk_bf16_f32 v108, v80, v81
	v_cvt_pk_bf16_f32 v109, v82, v83
	v_cvt_pk_bf16_f32 v110, v84, v85
	v_cvt_pk_bf16_f32 v111, v86, v87
	v_cndmask_b32_e64 v108, 0, v108, s[36:37]
	v_cndmask_b32_e64 v109, 0, v109, s[36:37]
	v_cndmask_b32_e64 v110, 0, v110, s[36:37]
	v_cndmask_b32_e64 v111, 0, v111, s[36:37]
	global_store_dwordx4 v[68:69], v[108:111], off
	v_lshl_add_u64 v[68:69], v[68:69], 0, s[38:39]
	v_sub_u32_e32 v65, 26, v62
	v_max_i32_e32 v65, 0, v65
	v_lshl_add_u32 v66, v65, 10, v64
	ds_read_b128 v[72:75], v66
	ds_read_b128 v[76:79], v66 offset:16
	ds_read_b128 v[80:83], v66 offset:512
	ds_read_b128 v[84:87], v66 offset:528
	s_waitcnt lgkmcnt(4)
	v_cmp_ge_u32_e64 s[36:37], 25, v62
	v_cvt_pk_bf16_f32 v104, v88, v89
	v_cvt_pk_bf16_f32 v105, v90, v91
	v_cvt_pk_bf16_f32 v106, v92, v93
	v_cvt_pk_bf16_f32 v107, v94, v95
	v_cndmask_b32_e64 v104, 0, v104, s[36:37]
	v_cndmask_b32_e64 v105, 0, v105, s[36:37]
	v_cndmask_b32_e64 v106, 0, v106, s[36:37]
	v_cndmask_b32_e64 v107, 0, v107, s[36:37]
	global_store_dwordx4 v[68:69], v[104:107], off
	v_lshl_add_u64 v[68:69], v[68:69], 0, s[38:39]
	v_cvt_pk_bf16_f32 v108, v96, v97
	v_cvt_pk_bf16_f32 v109, v98, v99
	v_cvt_pk_bf16_f32 v110, v100, v101
	v_cvt_pk_bf16_f32 v111, v102, v103
	v_cndmask_b32_e64 v108, 0, v108, s[36:37]
	v_cndmask_b32_e64 v109, 0, v109, s[36:37]
	v_cndmask_b32_e64 v110, 0, v110, s[36:37]
	v_cndmask_b32_e64 v111, 0, v111, s[36:37]
	global_store_dwordx4 v[68:69], v[108:111], off
	v_lshl_add_u64 v[68:69], v[68:69], 0, s[38:39]
	v_sub_u32_e32 v65, 27, v62
	v_max_i32_e32 v65, 0, v65
	v_lshl_add_u32 v66, v65, 10, v64
	ds_read_b128 v[88:91], v66
	ds_read_b128 v[92:95], v66 offset:16
	ds_read_b128 v[96:99], v66 offset:512
	ds_read_b128 v[100:103], v66 offset:528
	s_waitcnt lgkmcnt(4)
	v_cmp_ge_u32_e64 s[36:37], 26, v62
	v_cvt_pk_bf16_f32 v104, v72, v73
	v_cvt_pk_bf16_f32 v105, v74, v75
	v_cvt_pk_bf16_f32 v106, v76, v77
	v_cvt_pk_bf16_f32 v107, v78, v79
	v_cndmask_b32_e64 v104, 0, v104, s[36:37]
	v_cndmask_b32_e64 v105, 0, v105, s[36:37]
	v_cndmask_b32_e64 v106, 0, v106, s[36:37]
	v_cndmask_b32_e64 v107, 0, v107, s[36:37]
	global_store_dwordx4 v[68:69], v[104:107], off
	v_lshl_add_u64 v[68:69], v[68:69], 0, s[38:39]
	v_cvt_pk_bf16_f32 v108, v80, v81
	v_cvt_pk_bf16_f32 v109, v82, v83
	v_cvt_pk_bf16_f32 v110, v84, v85
	v_cvt_pk_bf16_f32 v111, v86, v87
	v_cndmask_b32_e64 v108, 0, v108, s[36:37]
	v_cndmask_b32_e64 v109, 0, v109, s[36:37]
	v_cndmask_b32_e64 v110, 0, v110, s[36:37]
	v_cndmask_b32_e64 v111, 0, v111, s[36:37]
	global_store_dwordx4 v[68:69], v[108:111], off
	v_lshl_add_u64 v[68:69], v[68:69], 0, s[38:39]
	v_sub_u32_e32 v65, 28, v62
	v_max_i32_e32 v65, 0, v65
	v_lshl_add_u32 v66, v65, 10, v64
	ds_read_b128 v[72:75], v66
	ds_read_b128 v[76:79], v66 offset:16
	ds_read_b128 v[80:83], v66 offset:512
	ds_read_b128 v[84:87], v66 offset:528
	s_waitcnt lgkmcnt(4)
	v_cmp_ge_u32_e64 s[36:37], 27, v62
	v_cvt_pk_bf16_f32 v104, v88, v89
	v_cvt_pk_bf16_f32 v105, v90, v91
	v_cvt_pk_bf16_f32 v106, v92, v93
	v_cvt_pk_bf16_f32 v107, v94, v95
	v_cndmask_b32_e64 v104, 0, v104, s[36:37]
	v_cndmask_b32_e64 v105, 0, v105, s[36:37]
	v_cndmask_b32_e64 v106, 0, v106, s[36:37]
	v_cndmask_b32_e64 v107, 0, v107, s[36:37]
	global_store_dwordx4 v[68:69], v[104:107], off
	v_lshl_add_u64 v[68:69], v[68:69], 0, s[38:39]
	v_cvt_pk_bf16_f32 v108, v96, v97
	v_cvt_pk_bf16_f32 v109, v98, v99
	v_cvt_pk_bf16_f32 v110, v100, v101
	v_cvt_pk_bf16_f32 v111, v102, v103
	v_cndmask_b32_e64 v108, 0, v108, s[36:37]
	v_cndmask_b32_e64 v109, 0, v109, s[36:37]
	v_cndmask_b32_e64 v110, 0, v110, s[36:37]
	v_cndmask_b32_e64 v111, 0, v111, s[36:37]
	global_store_dwordx4 v[68:69], v[108:111], off
	v_lshl_add_u64 v[68:69], v[68:69], 0, s[38:39]
	v_sub_u32_e32 v65, 29, v62
	v_max_i32_e32 v65, 0, v65
	v_lshl_add_u32 v66, v65, 10, v64
	ds_read_b128 v[88:91], v66
	ds_read_b128 v[92:95], v66 offset:16
	ds_read_b128 v[96:99], v66 offset:512
	ds_read_b128 v[100:103], v66 offset:528
	s_waitcnt lgkmcnt(4)
; DI u32x4 pack8(const float* f) { u32x4 w; w.x = pk2(f[0], f[1]); w.y = pk2(f[2], f[3]); w.z = pk2(f[4], f[5]); w.w = pk2(f[6], f[7]); return w; }
; DI void phase_s5pre(LAS unsigned char* lds, PP p, int l, int bid, int nblk) {
;     ...
;         for (int id = tid; id < 512 * 80; id += NTHR) { const int n = id / 80, oc = id % 80, t = n >> 4, ho = n & 15; float f[8];
;             if (oc < 64) { const int s = oc >> 1, hi0 = (oc & 1) * 8;
;                 for (int i = 0; i < 8; ++i) f[i] = (s <= t) ? kt[(t - s) * 256 + ho * 16 + hi0 + i] : 0.f;
;             } else { for (int i = 0; i < 8; ++i) { const int cc = (oc - 64) * 8 + i, ri = cc >> 6, pp = cc & 63;
;                 const float ar = apr[(t + 1) * 64 + pp], ai = api[(t + 1) * 64 + pp], cr = ccr[ho * 64 + pp], ci = cci[ho * 64 + pp];
;                 f[i] = ri == 0 ? (cr * ar - ci * ai) : -(cr * ai + ci * ar); } }
;             *(u32x4*)(bt2 + ((size_t)g * 512 + n) * 640 + oc * 8) = pack8(f); }
	v_cmp_ge_u32_e64 s[36:37], 28, v62
	v_cvt_pk_bf16_f32 v104, v72, v73
	v_cvt_pk_bf16_f32 v105, v74, v75
	v_cvt_pk_bf16_f32 v106, v76, v77
	v_cvt_pk_bf16_f32 v107, v78, v79
	v_cndmask_b32_e64 v104, 0, v104, s[36:37]
	v_cndmask_b32_e64 v105, 0, v105, s[36:37]
	v_cndmask_b32_e64 v106, 0, v106, s[36:37]
	v_cndmask_b32_e64 v107, 0, v107, s[36:37]
	global_store_dwordx4 v[68:69], v[104:107], off
	v_lshl_add_u64 v[68:69], v[68:69], 0, s[38:39]
	v_cvt_pk_bf16_f32 v108, v80, v81
	v_cvt_pk_bf16_f32 v109, v82, v83
	v_cvt_pk_bf16_f32 v110, v84, v85
	v_cvt_pk_bf16_f32 v111, v86, v87
	v_cndmask_b32_e64 v108, 0, v108, s[36:37]
	v_cndmask_b32_e64 v109, 0, v109, s[36:37]
	v_cndmask_b32_e64 v110, 0, v110, s[36:37]
	v_cndmask_b32_e64 v111, 0, v111, s[36:37]
	global_store_dwordx4 v[68:69], v[108:111], off
	v_lshl_add_u64 v[68:69], v[68:69], 0, s[38:39]
	v_sub_u32_e32 v65, 30, v62
	v_max_i32_e32 v65, 0, v65
	v_lshl_add_u32 v66, v65, 10, v64
	ds_read_b128 v[72:75], v66
	ds_read_b128 v[76:79], v66 offset:16
	ds_read_b128 v[80:83], v66 offset:512
	ds_read_b128 v[84:87], v66 offset:528
	s_waitcnt lgkmcnt(4)
	v_cmp_ge_u32_e64 s[36:37], 29, v62
	v_cvt_pk_bf16_f32 v104, v88, v89
	v_cvt_pk_bf16_f32 v105, v90, v91
	v_cvt_pk_bf16_f32 v106, v92, v93
	v_cvt_pk_bf16_f32 v107, v94, v95
	v_cndmask_b32_e64 v104, 0, v104, s[36:37]
	v_cndmask_b32_e64 v105, 0, v105, s[36:37]
	v_cndmask_b32_e64 v106, 0, v106, s[36:37]
	v_cndmask_b32_e64 v107, 0, v107, s[36:37]
	global_store_dwordx4 v[68:69], v[104:107], off
	v_lshl_add_u64 v[68:69], v[68:69], 0, s[38:39]
	v_cvt_pk_bf16_f32 v108, v96, v97
	v_cvt_pk_bf16_f32 v109, v98, v99
	v_cvt_pk_bf16_f32 v110, v100, v101
	v_cvt_pk_bf16_f32 v111, v102, v103
	v_cndmask_b32_e64 v108, 0, v108, s[36:37]
	v_cndmask_b32_e64 v109, 0, v109, s[36:37]
	v_cndmask_b32_e64 v110, 0, v110, s[36:37]
	v_cndmask_b32_e64 v111, 0, v111, s[36:37]
	global_store_dwordx4 v[68:69], v[108:111], off
	v_lshl_add_u64 v[68:69], v[68:69], 0, s[38:39]
	v_sub_u32_e32 v65, 31, v62
	v_max_i32_e32 v65, 0, v65
	v_lshl_add_u32 v66, v65, 10, v64
	ds_read_b128 v[88:91], v66
	ds_read_b128 v[92:95], v66 offset:16
	ds_read_b128 v[96:99], v66 offset:512
	ds_read_b128 v[100:103], v66 offset:528
	s_waitcnt lgkmcnt(4)
	v_cmp_ge_u32_e64 s[36:37], 30, v62
	v_cvt_pk_bf16_f32 v104, v72, v73
	v_cvt_pk_bf16_f32 v105, v74, v75
	v_cvt_pk_bf16_f32 v106, v76, v77
	v_cvt_pk_bf16_f32 v107, v78, v79
	v_cndmask_b32_e64 v104, 0, v104, s[36:37]
	v_cndmask_b32_e64 v105, 0, v105, s[36:37]
	v_cndmask_b32_e64 v106, 0, v106, s[36:37]
	v_cndmask_b32_e64 v107, 0, v107, s[36:37]
	global_store_dwordx4 v[68:69], v[104:107], off
	v_lshl_add_u64 v[68:69], v[68:69], 0, s[38:39]
	v_cvt_pk_bf16_f32 v108, v80, v81
	v_cvt_pk_bf16_f32 v109, v82, v83
	v_cvt_pk_bf16_f32 v110, v84, v85
	v_cvt_pk_bf16_f32 v111, v86, v87
	v_cndmask_b32_e64 v108, 0, v108, s[36:37]
	v_cndmask_b32_e64 v109, 0, v109, s[36:37]
	v_cndmask_b32_e64 v110, 0, v110, s[36:37]
	v_cndmask_b32_e64 v111, 0, v111, s[36:37]
	global_store_dwordx4 v[68:69], v[108:111], off
	v_lshl_add_u64 v[68:69], v[68:69], 0, s[38:39]
	s_waitcnt lgkmcnt(0)
	v_cmp_ge_u32_e64 s[36:37], 31, v62
	v_cvt_pk_bf16_f32 v104, v88, v89
	v_cvt_pk_bf16_f32 v105, v90, v91
	v_cvt_pk_bf16_f32 v106, v92, v93
	v_cvt_pk_bf16_f32 v107, v94, v95
	v_cndmask_b32_e64 v104, 0, v104, s[36:37]
	v_cndmask_b32_e64 v105, 0, v105, s[36:37]
	v_cndmask_b32_e64 v106, 0, v106, s[36:37]
	v_cndmask_b32_e64 v107, 0, v107, s[36:37]
	global_store_dwordx4 v[68:69], v[104:107], off
	v_lshl_add_u64 v[68:69], v[68:69], 0, s[38:39]
	v_cvt_pk_bf16_f32 v108, v96, v97
	v_cvt_pk_bf16_f32 v109, v98, v99
	v_cvt_pk_bf16_f32 v110, v100, v101
	v_cvt_pk_bf16_f32 v111, v102, v103
	v_cndmask_b32_e64 v108, 0, v108, s[36:37]
	v_cndmask_b32_e64 v109, 0, v109, s[36:37]
	v_cndmask_b32_e64 v110, 0, v110, s[36:37]
	v_cndmask_b32_e64 v111, 0, v111, s[36:37]
	global_store_dwordx4 v[68:69], v[108:111], off
	v_lshl_add_u64 v[68:69], v[68:69], 0, s[38:39]
	ds_read_b128 v[132:135], v112 offset:0
	ds_read_b128 v[136:139], v112 offset:16
	ds_read_b128 v[140:143], v113 offset:0
	ds_read_b128 v[144:147], v113 offset:16
	s_waitcnt lgkmcnt(0)
	v_mul_f32_e32 v148, v140, v124
	v_mul_f32_e32 v149, v141, v125
	v_mul_f32_e32 v150, v142, v126
	v_mul_f32_e32 v151, v143, v127
	v_mul_f32_e32 v152, v144, v128
	v_mul_f32_e32 v153, v145, v129
	v_mul_f32_e32 v154, v146, v130
	v_mul_f32_e32 v155, v147, v131
	v_fma_f32 v156, v132, v116, -v148
	v_fma_f32 v157, v133, v117, -v149
	v_fma_f32 v158, v134, v118, -v150
	v_fma_f32 v159, v135, v119, -v151
	v_fma_f32 v160, v136, v120, -v152
	v_fma_f32 v161, v137, v121, -v153
	v_fma_f32 v162, v138, v122, -v154
	v_fma_f32 v163, v139, v123, -v155
	v_cvt_pk_bf16_f32 v164, v156, v157
	v_cvt_pk_bf16_f32 v165, v158, v159
	v_cvt_pk_bf16_f32 v166, v160, v161
	v_cvt_pk_bf16_f32 v167, v162, v163
	global_store_dwordx4 v[172:173], v[164:167], off
	v_lshl_add_u64 v[172:173], v[172:173], 0, s[40:41]
	ds_read_b128 v[132:135], v112 offset:512
	ds_read_b128 v[136:139], v112 offset:528
	ds_read_b128 v[140:143], v113 offset:512
	ds_read_b128 v[144:147], v113 offset:528
	s_waitcnt lgkmcnt(0)
	v_mul_f32_e32 v148, v140, v124
	v_mul_f32_e32 v149, v141, v125
	v_mul_f32_e32 v150, v142, v126
	v_mul_f32_e32 v151, v143, v127
	v_mul_f32_e32 v152, v144, v128
	v_mul_f32_e32 v153, v145, v129
	v_mul_f32_e32 v154, v146, v130
	v_mul_f32_e32 v155, v147, v131
	v_fma_f32 v156, v132, v116, -v148
	v_fma_f32 v157, v133, v117, -v149
	v_fma_f32 v158, v134, v118, -v150
	v_fma_f32 v159, v135, v119, -v151
	v_fma_f32 v160, v136, v120, -v152
	v_fma_f32 v161, v137, v121, -v153
	v_fma_f32 v162, v138, v122, -v154
	v_fma_f32 v163, v139, v123, -v155
	v_cvt_pk_bf16_f32 v168, v156, v157
	v_cvt_pk_bf16_f32 v169, v158, v159
	v_cvt_pk_bf16_f32 v170, v160, v161
	v_cvt_pk_bf16_f32 v171, v162, v163
	global_store_dwordx4 v[172:173], v[168:171], off
	v_lshl_add_u64 v[172:173], v[172:173], 0, s[40:41]
	ds_read_b128 v[132:135], v112 offset:1024
	ds_read_b128 v[136:139], v112 offset:1040
	ds_read_b128 v[140:143], v113 offset:1024
	ds_read_b128 v[144:147], v113 offset:1040
	s_waitcnt lgkmcnt(0)
; DI u32x4 pack8(const float* f) { u32x4 w; w.x = pk2(f[0], f[1]); w.y = pk2(f[2], f[3]); w.z = pk2(f[4], f[5]); w.w = pk2(f[6], f[7]); return w; }
; DI void phase_s5pre(LAS unsigned char* lds, PP p, int l, int bid, int nblk) {
;     ...
;             } else { for (int i = 0; i < 8; ++i) { const int cc = (oc - 64) * 8 + i, ri = cc >> 6, pp = cc & 63;
;                 const float ar = apr[(t + 1) * 64 + pp], ai = api[(t + 1) * 64 + pp], cr = ccr[ho * 64 + pp], ci = cci[ho * 64 + pp];
;                 f[i] = ri == 0 ? (cr * ar - ci * ai) : -(cr * ai + ci * ar); } }
;             *(u32x4*)(bt2 + ((size_t)g * 512 + n) * 640 + oc * 8) = pack8(f); }
	v_mul_f32_e32 v148, v140, v124
	v_mul_f32_e32 v149, v141, v125
	v_mul_f32_e32 v150, v142, v126
	v_mul_f32_e32 v151, v143, v127
	v_mul_f32_e32 v152, v144, v128
	v_mul_f32_e32 v153, v145, v129
	v_mul_f32_e32 v154, v146, v130
	v_mul_f32_e32 v155, v147, v131
	v_fma_f32 v156, v132, v116, -v148
	v_fma_f32 v157, v133, v117, -v149
	v_fma_f32 v158, v134, v118, -v150
	v_fma_f32 v159, v135, v119, -v151
	v_fma_f32 v160, v136, v120, -v152
	v_fma_f32 v161, v137, v121, -v153
	v_fma_f32 v162, v138, v122, -v154
	v_fma_f32 v163, v139, v123, -v155
	v_cvt_pk_bf16_f32 v164, v156, v157
	v_cvt_pk_bf16_f32 v165, v158, v159
	v_cvt_pk_bf16_f32 v166, v160, v161
	v_cvt_pk_bf16_f32 v167, v162, v163
	global_store_dwordx4 v[172:173], v[164:167], off
	v_lshl_add_u64 v[172:173], v[172:173], 0, s[40:41]
	ds_read_b128 v[132:135], v112 offset:1536
	ds_read_b128 v[136:139], v112 offset:1552
	ds_read_b128 v[140:143], v113 offset:1536
	ds_read_b128 v[144:147], v113 offset:1552
	s_waitcnt lgkmcnt(0)
	v_mul_f32_e32 v148, v140, v124
	v_mul_f32_e32 v149, v141, v125
	v_mul_f32_e32 v150, v142, v126
	v_mul_f32_e32 v151, v143, v127
	v_mul_f32_e32 v152, v144, v128
	v_mul_f32_e32 v153, v145, v129
	v_mul_f32_e32 v154, v146, v130
	v_mul_f32_e32 v155, v147, v131
	v_fma_f32 v156, v132, v116, -v148
	v_fma_f32 v157, v133, v117, -v149
	v_fma_f32 v158, v134, v118, -v150
	v_fma_f32 v159, v135, v119, -v151
	v_fma_f32 v160, v136, v120, -v152
	v_fma_f32 v161, v137, v121, -v153
	v_fma_f32 v162, v138, v122, -v154
	v_fma_f32 v163, v139, v123, -v155
	v_cvt_pk_bf16_f32 v168, v156, v157
	v_cvt_pk_bf16_f32 v169, v158, v159
	v_cvt_pk_bf16_f32 v170, v160, v161
	v_cvt_pk_bf16_f32 v171, v162, v163
	global_store_dwordx4 v[172:173], v[168:171], off
	v_lshl_add_u64 v[172:173], v[172:173], 0, s[40:41]
	ds_read_b128 v[132:135], v112 offset:2048
	ds_read_b128 v[136:139], v112 offset:2064
	ds_read_b128 v[140:143], v113 offset:2048
	ds_read_b128 v[144:147], v113 offset:2064
	s_waitcnt lgkmcnt(0)
	v_mul_f32_e32 v148, v140, v124
	v_mul_f32_e32 v149, v141, v125
	v_mul_f32_e32 v150, v142, v126
	v_mul_f32_e32 v151, v143, v127
	v_mul_f32_e32 v152, v144, v128
	v_mul_f32_e32 v153, v145, v129
	v_mul_f32_e32 v154, v146, v130
	v_mul_f32_e32 v155, v147, v131
	v_fma_f32 v156, v132, v116, -v148
	v_fma_f32 v157, v133, v117, -v149
	v_fma_f32 v158, v134, v118, -v150
	v_fma_f32 v159, v135, v119, -v151
	v_fma_f32 v160, v136, v120, -v152
	v_fma_f32 v161, v137, v121, -v153
	v_fma_f32 v162, v138, v122, -v154
	v_fma_f32 v163, v139, v123, -v155
	v_cvt_pk_bf16_f32 v164, v156, v157
	v_cvt_pk_bf16_f32 v165, v158, v159
	v_cvt_pk_bf16_f32 v166, v160, v161
	v_cvt_pk_bf16_f32 v167, v162, v163
	global_store_dwordx4 v[172:173], v[164:167], off
	v_lshl_add_u64 v[172:173], v[172:173], 0, s[40:41]
	ds_read_b128 v[132:135], v112 offset:2560
	ds_read_b128 v[136:139], v112 offset:2576
	ds_read_b128 v[140:143], v113 offset:2560
	ds_read_b128 v[144:147], v113 offset:2576
	s_waitcnt lgkmcnt(0)
	v_mul_f32_e32 v148, v140, v124
	v_mul_f32_e32 v149, v141, v125
	v_mul_f32_e32 v150, v142, v126
	v_mul_f32_e32 v151, v143, v127
	v_mul_f32_e32 v152, v144, v128
	v_mul_f32_e32 v153, v145, v129
	v_mul_f32_e32 v154, v146, v130
	v_mul_f32_e32 v155, v147, v131
	v_fma_f32 v156, v132, v116, -v148
	v_fma_f32 v157, v133, v117, -v149
	v_fma_f32 v158, v134, v118, -v150
	v_fma_f32 v159, v135, v119, -v151
	v_fma_f32 v160, v136, v120, -v152
	v_fma_f32 v161, v137, v121, -v153
	v_fma_f32 v162, v138, v122, -v154
	v_fma_f32 v163, v139, v123, -v155
	v_cvt_pk_bf16_f32 v168, v156, v157
	v_cvt_pk_bf16_f32 v169, v158, v159
	v_cvt_pk_bf16_f32 v170, v160, v161
	v_cvt_pk_bf16_f32 v171, v162, v163
	global_store_dwordx4 v[172:173], v[168:171], off
	v_lshl_add_u64 v[172:173], v[172:173], 0, s[40:41]
	ds_read_b128 v[132:135], v112 offset:3072
	ds_read_b128 v[136:139], v112 offset:3088
	ds_read_b128 v[140:143], v113 offset:3072
	ds_read_b128 v[144:147], v113 offset:3088
	s_waitcnt lgkmcnt(0)
	v_mul_f32_e32 v148, v140, v124
	v_mul_f32_e32 v149, v141, v125
	v_mul_f32_e32 v150, v142, v126
	v_mul_f32_e32 v151, v143, v127
	v_mul_f32_e32 v152, v144, v128
	v_mul_f32_e32 v153, v145, v129
	v_mul_f32_e32 v154, v146, v130
	v_mul_f32_e32 v155, v147, v131
	v_fma_f32 v156, v132, v116, -v148
	v_fma_f32 v157, v133, v117, -v149
	v_fma_f32 v158, v134, v118, -v150
	v_fma_f32 v159, v135, v119, -v151
	v_fma_f32 v160, v136, v120, -v152
	v_fma_f32 v161, v137, v121, -v153
	v_fma_f32 v162, v138, v122, -v154
	v_fma_f32 v163, v139, v123, -v155
	v_cvt_pk_bf16_f32 v164, v156, v157
	v_cvt_pk_bf16_f32 v165, v158, v159
	v_cvt_pk_bf16_f32 v166, v160, v161
	v_cvt_pk_bf16_f32 v167, v162, v163
	global_store_dwordx4 v[172:173], v[164:167], off
	v_lshl_add_u64 v[172:173], v[172:173], 0, s[40:41]
	ds_read_b128 v[132:135], v112 offset:3584
	ds_read_b128 v[136:139], v112 offset:3600
	ds_read_b128 v[140:143], v113 offset:3584
	ds_read_b128 v[144:147], v113 offset:3600
	s_waitcnt lgkmcnt(0)
	v_mul_f32_e32 v148, v140, v124
	v_mul_f32_e32 v149, v141, v125
	v_mul_f32_e32 v150, v142, v126
	v_mul_f32_e32 v151, v143, v127
	v_mul_f32_e32 v152, v144, v128
	v_mul_f32_e32 v153, v145, v129
	v_mul_f32_e32 v154, v146, v130
	v_mul_f32_e32 v155, v147, v131
	v_fma_f32 v156, v132, v116, -v148
	v_fma_f32 v157, v133, v117, -v149
	v_fma_f32 v158, v134, v118, -v150
	v_fma_f32 v159, v135, v119, -v151
	v_fma_f32 v160, v136, v120, -v152
	v_fma_f32 v161, v137, v121, -v153
	v_fma_f32 v162, v138, v122, -v154
	v_fma_f32 v163, v139, v123, -v155
	v_cvt_pk_bf16_f32 v168, v156, v157
	v_cvt_pk_bf16_f32 v169, v158, v159
	v_cvt_pk_bf16_f32 v170, v160, v161
	v_cvt_pk_bf16_f32 v171, v162, v163
	global_store_dwordx4 v[172:173], v[168:171], off
	v_lshl_add_u64 v[172:173], v[172:173], 0, s[40:41]
	ds_read_b128 v[132:135], v112 offset:4096
	ds_read_b128 v[136:139], v112 offset:4112
	ds_read_b128 v[140:143], v113 offset:4096
	ds_read_b128 v[144:147], v113 offset:4112
	s_waitcnt lgkmcnt(0)
; DI u32x4 pack8(const float* f) { u32x4 w; w.x = pk2(f[0], f[1]); w.y = pk2(f[2], f[3]); w.z = pk2(f[4], f[5]); w.w = pk2(f[6], f[7]); return w; }
; DI void phase_s5pre(LAS unsigned char* lds, PP p, int l, int bid, int nblk) {
;     ...
;             } else { for (int i = 0; i < 8; ++i) { const int cc = (oc - 64) * 8 + i, ri = cc >> 6, pp = cc & 63;
;                 const float ar = apr[(t + 1) * 64 + pp], ai = api[(t + 1) * 64 + pp], cr = ccr[ho * 64 + pp], ci = cci[ho * 64 + pp];
;                 f[i] = ri == 0 ? (cr * ar - ci * ai) : -(cr * ai + ci * ar); } }
;             *(u32x4*)(bt2 + ((size_t)g * 512 + n) * 640 + oc * 8) = pack8(f); }
	v_mul_f32_e32 v148, v140, v124
	v_mul_f32_e32 v149, v141, v125
	v_mul_f32_e32 v150, v142, v126
	v_mul_f32_e32 v151, v143, v127
	v_mul_f32_e32 v152, v144, v128
	v_mul_f32_e32 v153, v145, v129
	v_mul_f32_e32 v154, v146, v130
	v_mul_f32_e32 v155, v147, v131
	v_fma_f32 v156, v132, v116, -v148
	v_fma_f32 v157, v133, v117, -v149
	v_fma_f32 v158, v134, v118, -v150
	v_fma_f32 v159, v135, v119, -v151
	v_fma_f32 v160, v136, v120, -v152
	v_fma_f32 v161, v137, v121, -v153
	v_fma_f32 v162, v138, v122, -v154
	v_fma_f32 v163, v139, v123, -v155
	v_cvt_pk_bf16_f32 v164, v156, v157
	v_cvt_pk_bf16_f32 v165, v158, v159
	v_cvt_pk_bf16_f32 v166, v160, v161
	v_cvt_pk_bf16_f32 v167, v162, v163
	global_store_dwordx4 v[172:173], v[164:167], off
	v_lshl_add_u64 v[172:173], v[172:173], 0, s[40:41]
	ds_read_b128 v[132:135], v112 offset:4608
	ds_read_b128 v[136:139], v112 offset:4624
	ds_read_b128 v[140:143], v113 offset:4608
	ds_read_b128 v[144:147], v113 offset:4624
	s_waitcnt lgkmcnt(0)
	v_mul_f32_e32 v148, v140, v124
	v_mul_f32_e32 v149, v141, v125
	v_mul_f32_e32 v150, v142, v126
	v_mul_f32_e32 v151, v143, v127
	v_mul_f32_e32 v152, v144, v128
	v_mul_f32_e32 v153, v145, v129
	v_mul_f32_e32 v154, v146, v130
	v_mul_f32_e32 v155, v147, v131
	v_fma_f32 v156, v132, v116, -v148
	v_fma_f32 v157, v133, v117, -v149
	v_fma_f32 v158, v134, v118, -v150
	v_fma_f32 v159, v135, v119, -v151
	v_fma_f32 v160, v136, v120, -v152
	v_fma_f32 v161, v137, v121, -v153
	v_fma_f32 v162, v138, v122, -v154
	v_fma_f32 v163, v139, v123, -v155
	v_cvt_pk_bf16_f32 v168, v156, v157
	v_cvt_pk_bf16_f32 v169, v158, v159
	v_cvt_pk_bf16_f32 v170, v160, v161
	v_cvt_pk_bf16_f32 v171, v162, v163
	global_store_dwordx4 v[172:173], v[168:171], off
	v_lshl_add_u64 v[172:173], v[172:173], 0, s[40:41]
	ds_read_b128 v[132:135], v112 offset:5120
	ds_read_b128 v[136:139], v112 offset:5136
	ds_read_b128 v[140:143], v113 offset:5120
	ds_read_b128 v[144:147], v113 offset:5136
	s_waitcnt lgkmcnt(0)
	v_mul_f32_e32 v148, v140, v124
	v_mul_f32_e32 v149, v141, v125
	v_mul_f32_e32 v150, v142, v126
	v_mul_f32_e32 v151, v143, v127
	v_mul_f32_e32 v152, v144, v128
	v_mul_f32_e32 v153, v145, v129
	v_mul_f32_e32 v154, v146, v130
	v_mul_f32_e32 v155, v147, v131
	v_fma_f32 v156, v132, v116, -v148
	v_fma_f32 v157, v133, v117, -v149
	v_fma_f32 v158, v134, v118, -v150
	v_fma_f32 v159, v135, v119, -v151
	v_fma_f32 v160, v136, v120, -v152
	v_fma_f32 v161, v137, v121, -v153
	v_fma_f32 v162, v138, v122, -v154
	v_fma_f32 v163, v139, v123, -v155
	v_cvt_pk_bf16_f32 v164, v156, v157
	v_cvt_pk_bf16_f32 v165, v158, v159
	v_cvt_pk_bf16_f32 v166, v160, v161
	v_cvt_pk_bf16_f32 v167, v162, v163
	global_store_dwordx4 v[172:173], v[164:167], off
	v_lshl_add_u64 v[172:173], v[172:173], 0, s[40:41]
	ds_read_b128 v[132:135], v112 offset:5632
	ds_read_b128 v[136:139], v112 offset:5648
	ds_read_b128 v[140:143], v113 offset:5632
	ds_read_b128 v[144:147], v113 offset:5648
	s_waitcnt lgkmcnt(0)
	v_mul_f32_e32 v148, v140, v124
	v_mul_f32_e32 v149, v141, v125
	v_mul_f32_e32 v150, v142, v126
	v_mul_f32_e32 v151, v143, v127
	v_mul_f32_e32 v152, v144, v128
	v_mul_f32_e32 v153, v145, v129
	v_mul_f32_e32 v154, v146, v130
	v_mul_f32_e32 v155, v147, v131
	v_fma_f32 v156, v132, v116, -v148
	v_fma_f32 v157, v133, v117, -v149
	v_fma_f32 v158, v134, v118, -v150
	v_fma_f32 v159, v135, v119, -v151
	v_fma_f32 v160, v136, v120, -v152
	v_fma_f32 v161, v137, v121, -v153
	v_fma_f32 v162, v138, v122, -v154
	v_fma_f32 v163, v139, v123, -v155
	v_cvt_pk_bf16_f32 v168, v156, v157
	v_cvt_pk_bf16_f32 v169, v158, v159
	v_cvt_pk_bf16_f32 v170, v160, v161
	v_cvt_pk_bf16_f32 v171, v162, v163
	global_store_dwordx4 v[172:173], v[168:171], off
	v_lshl_add_u64 v[172:173], v[172:173], 0, s[40:41]
	ds_read_b128 v[132:135], v112 offset:6144
	ds_read_b128 v[136:139], v112 offset:6160
	ds_read_b128 v[140:143], v113 offset:6144
	ds_read_b128 v[144:147], v113 offset:6160
	s_waitcnt lgkmcnt(0)
; DI u32x4 pack8(const float* f) { u32x4 w; w.x = pk2(f[0], f[1]); w.y = pk2(f[2], f[3]); w.z = pk2(f[4], f[5]); w.w = pk2(f[6], f[7]); return w; }
; DI void phase_s5pre(LAS unsigned char* lds, PP p, int l, int bid, int nblk) {
;     ...
;             } else { for (int i = 0; i < 8; ++i) { const int cc = (oc - 64) * 8 + i, ri = cc >> 6, pp = cc & 63;
;                 const float ar = apr[(t + 1) * 64 + pp], ai = api[(t + 1) * 64 + pp], cr = ccr[ho * 64 + pp], ci = cci[ho * 64 + pp];
;                 f[i] = ri == 0 ? (cr * ar - ci * ai) : -(cr * ai + ci * ar); } }
;             *(u32x4*)(bt2 + ((size_t)g * 512 + n) * 640 + oc * 8) = pack8(f); }
	v_mul_f32_e32 v148, v140, v124
	v_mul_f32_e32 v149, v141, v125
	v_mul_f32_e32 v150, v142, v126
	v_mul_f32_e32 v151, v143, v127
	v_mul_f32_e32 v152, v144, v128
	v_mul_f32_e32 v153, v145, v129
	v_mul_f32_e32 v154, v146, v130
	v_mul_f32_e32 v155, v147, v131
	v_fma_f32 v156, v132, v116, -v148
	v_fma_f32 v157, v133, v117, -v149
	v_fma_f32 v158, v134, v118, -v150
	v_fma_f32 v159, v135, v119, -v151
	v_fma_f32 v160, v136, v120, -v152
	v_fma_f32 v161, v137, v121, -v153
	v_fma_f32 v162, v138, v122, -v154
	v_fma_f32 v163, v139, v123, -v155
	v_cvt_pk_bf16_f32 v164, v156, v157
	v_cvt_pk_bf16_f32 v165, v158, v159
	v_cvt_pk_bf16_f32 v166, v160, v161
	v_cvt_pk_bf16_f32 v167, v162, v163
	global_store_dwordx4 v[172:173], v[164:167], off
	v_lshl_add_u64 v[172:173], v[172:173], 0, s[40:41]
	ds_read_b128 v[132:135], v112 offset:6656
	ds_read_b128 v[136:139], v112 offset:6672
	ds_read_b128 v[140:143], v113 offset:6656
	ds_read_b128 v[144:147], v113 offset:6672
	s_waitcnt lgkmcnt(0)
	v_mul_f32_e32 v148, v140, v124
	v_mul_f32_e32 v149, v141, v125
	v_mul_f32_e32 v150, v142, v126
	v_mul_f32_e32 v151, v143, v127
	v_mul_f32_e32 v152, v144, v128
	v_mul_f32_e32 v153, v145, v129
	v_mul_f32_e32 v154, v146, v130
	v_mul_f32_e32 v155, v147, v131
	v_fma_f32 v156, v132, v116, -v148
	v_fma_f32 v157, v133, v117, -v149
	v_fma_f32 v158, v134, v118, -v150
	v_fma_f32 v159, v135, v119, -v151
	v_fma_f32 v160, v136, v120, -v152
	v_fma_f32 v161, v137, v121, -v153
	v_fma_f32 v162, v138, v122, -v154
	v_fma_f32 v163, v139, v123, -v155
	v_cvt_pk_bf16_f32 v168, v156, v157
	v_cvt_pk_bf16_f32 v169, v158, v159
	v_cvt_pk_bf16_f32 v170, v160, v161
	v_cvt_pk_bf16_f32 v171, v162, v163
	global_store_dwordx4 v[172:173], v[168:171], off
	v_lshl_add_u64 v[172:173], v[172:173], 0, s[40:41]
	ds_read_b128 v[132:135], v112 offset:7168
	ds_read_b128 v[136:139], v112 offset:7184
	ds_read_b128 v[140:143], v113 offset:7168
	ds_read_b128 v[144:147], v113 offset:7184
	s_waitcnt lgkmcnt(0)
	v_mul_f32_e32 v148, v140, v124
	v_mul_f32_e32 v149, v141, v125
	v_mul_f32_e32 v150, v142, v126
	v_mul_f32_e32 v151, v143, v127
	v_mul_f32_e32 v152, v144, v128
	v_mul_f32_e32 v153, v145, v129
	v_mul_f32_e32 v154, v146, v130
	v_mul_f32_e32 v155, v147, v131
	v_fma_f32 v156, v132, v116, -v148
	v_fma_f32 v157, v133, v117, -v149
	v_fma_f32 v158, v134, v118, -v150
	v_fma_f32 v159, v135, v119, -v151
	v_fma_f32 v160, v136, v120, -v152
	v_fma_f32 v161, v137, v121, -v153
	v_fma_f32 v162, v138, v122, -v154
	v_fma_f32 v163, v139, v123, -v155
	v_cvt_pk_bf16_f32 v164, v156, v157
	v_cvt_pk_bf16_f32 v165, v158, v159
	v_cvt_pk_bf16_f32 v166, v160, v161
	v_cvt_pk_bf16_f32 v167, v162, v163
	global_store_dwordx4 v[172:173], v[164:167], off
	v_lshl_add_u64 v[172:173], v[172:173], 0, s[40:41]
	ds_read_b128 v[132:135], v112 offset:7680
	ds_read_b128 v[136:139], v112 offset:7696
	ds_read_b128 v[140:143], v113 offset:7680
	ds_read_b128 v[144:147], v113 offset:7696
	s_waitcnt lgkmcnt(0)
	v_mul_f32_e32 v148, v140, v124
	v_mul_f32_e32 v149, v141, v125
	v_mul_f32_e32 v150, v142, v126
	v_mul_f32_e32 v151, v143, v127
	v_mul_f32_e32 v152, v144, v128
	v_mul_f32_e32 v153, v145, v129
	v_mul_f32_e32 v154, v146, v130
	v_mul_f32_e32 v155, v147, v131
	v_fma_f32 v156, v132, v116, -v148
	v_fma_f32 v157, v133, v117, -v149
	v_fma_f32 v158, v134, v118, -v150
	v_fma_f32 v159, v135, v119, -v151
	v_fma_f32 v160, v136, v120, -v152
	v_fma_f32 v161, v137, v121, -v153
	v_fma_f32 v162, v138, v122, -v154
	v_fma_f32 v163, v139, v123, -v155
	v_cvt_pk_bf16_f32 v168, v156, v157
	v_cvt_pk_bf16_f32 v169, v158, v159
	v_cvt_pk_bf16_f32 v170, v160, v161
	v_cvt_pk_bf16_f32 v171, v162, v163
	global_store_dwordx4 v[172:173], v[168:171], off
	v_lshl_add_u64 v[172:173], v[172:173], 0, s[40:41]
